# write-through (sc1) stores for data published at the 3 remaining full barriers (P0 weights, P3 QKV, P4 outputs) on top of XCD-local seams
# speedup vs baseline: 1.0417x; 1.0075x over previous
; #define LAS __attribute__((address_space(3)))
; __device__ __forceinline__ unsigned pk2(float lo, float hi) { f32x2 v = {lo, hi}; bf2_t b = __builtin_convertvector(v, bf2_t); return __builtin_bit_cast(unsigned, b); }
;     ...
;       for (int i = 0; i < 8; ++i) { const int kk = 8 * i + (lane >> 3); LAS float* d = scr + kk * 33 + 4 * (lane & 7); d[0] = wv[i][0] * gv[i]; d[1] = wv[i][1] * gv[i]; d[2] = wv[i][2] * gv[i]; d[3] = wv[i][3] * gv[i]; } }
;     asm volatile("s_waitcnt lgkmcnt(0)" ::: "memory");
;     const int c = lane & 7; const int r0 = dst_row(dmode, n0);
; #pragma unroll
;     for (int j = 0; j < 4; ++j) { const int n = (lane >> 3) + 8 * j; const LAS float* s = scr + (8 * c) * 33 + n;
;         u32x4 o; o.x = pk2(s[0 * 33], s[1 * 33]); o.y = pk2(s[2 * 33], s[3 * 33]); o.z = pk2(s[4 * 33], s[5 * 33]); o.w = pk2(s[6 * 33], s[7 * 33]);
;         *(u32x4*)(WT + (size_t)(r0 + n) * pitch + k0 + 8 * c) = o; }
.LBB0_13:
	s_waitcnt vmcnt(7)
	v_pk_mul_f32 v[2:3], v[2:3], v[126:127] op_sel_hi:[1,0]
	v_add_u32_e32 v130, v105, v141
	ds_write2_b32 v130, v2, v3 offset1:1
	v_pk_mul_f32 v[2:3], v[4:5], v[126:127] op_sel_hi:[1,0]
	ds_write2_b32 v130, v2, v3 offset0:2 offset1:3
	s_waitcnt vmcnt(6)
	v_pk_mul_f32 v[2:3], v[6:7], v[34:35] op_sel_hi:[1,0]
	v_add_u32_e32 v4, 0x420, v130
	ds_write2_b32 v4, v2, v3 offset1:1
	v_pk_mul_f32 v[2:3], v[8:9], v[34:35] op_sel_hi:[1,0]
	v_add_u32_e32 v4, 0x428, v130
	ds_write2_b32 v4, v2, v3 offset1:1
	s_waitcnt vmcnt(5)
	v_pk_mul_f32 v[2:3], v[10:11], v[132:133] op_sel_hi:[1,0]
	v_add_u32_e32 v4, 0x840, v130
	ds_write2_b32 v4, v2, v3 offset1:1
	v_pk_mul_f32 v[2:3], v[12:13], v[132:133] op_sel_hi:[1,0]
	v_add_u32_e32 v4, 0x848, v130
	ds_write2_b32 v4, v2, v3 offset1:1
	s_waitcnt vmcnt(4)
	v_pk_mul_f32 v[2:3], v[14:15], v[124:125] op_sel_hi:[1,0]
	v_add_u32_e32 v4, 0xc60, v130
	ds_write2_b32 v4, v2, v3 offset1:1
	v_pk_mul_f32 v[2:3], v[16:17], v[124:125] op_sel_hi:[1,0]
	v_add_u32_e32 v4, 0xc68, v130
	ds_write2_b32 v4, v2, v3 offset1:1
	s_waitcnt vmcnt(3)
	v_pk_mul_f32 v[2:3], v[18:19], v[136:137] op_sel_hi:[1,0]
	v_add_u32_e32 v4, 0x1080, v130
	ds_write2_b32 v4, v2, v3 offset1:1
	v_pk_mul_f32 v[2:3], v[20:21], v[136:137] op_sel_hi:[1,0]
	v_add_u32_e32 v4, 0x1088, v130
	ds_write2_b32 v4, v2, v3 offset1:1
	s_waitcnt vmcnt(2)
	v_pk_mul_f32 v[2:3], v[22:23], v[128:129] op_sel_hi:[1,0]
	v_add_u32_e32 v4, 0x14a0, v130
	ds_write2_b32 v4, v2, v3 offset1:1
	v_pk_mul_f32 v[2:3], v[24:25], v[128:129] op_sel_hi:[1,0]
	v_add_u32_e32 v4, 0x14a8, v130
	ds_write2_b32 v4, v2, v3 offset1:1
	s_waitcnt vmcnt(1)
	v_pk_mul_f32 v[2:3], v[26:27], v[138:139] op_sel_hi:[1,0]
	v_add_u32_e32 v4, 0x18c0, v130
	ds_write2_b32 v4, v2, v3 offset1:1
	v_pk_mul_f32 v[2:3], v[28:29], v[138:139] op_sel_hi:[1,0]
	v_add_u32_e32 v4, 0x18c8, v130
	ds_write2_b32 v4, v2, v3 offset1:1
	s_waitcnt vmcnt(0)
	v_pk_mul_f32 v[2:3], v[30:31], v[134:135] op_sel_hi:[1,0]
	v_add_u32_e32 v4, 0x1ce0, v130
	ds_write2_b32 v4, v2, v3 offset1:1
	v_pk_mul_f32 v[2:3], v[32:33], v[134:135] op_sel_hi:[1,0]
	v_add_u32_e32 v4, 0x1ce8, v130
	ds_write2_b32 v4, v2, v3 offset1:1
	s_mulk_i32 s22, 0xea00
	s_waitcnt lgkmcnt(0)
	s_add_i32 s8, s92, s22
	s_and_b32 s8, s8, 0xffffff00
	s_and_b32 s9, s76, 0x60
	ds_read2_b32 v[6:7], v155 offset0:33 offset1:41
	ds_read2_b32 v[8:9], v155 offset1:8
	ds_read2_b32 v[10:11], v155 offset0:66 offset1:74
	ds_read2_b32 v[12:13], v155 offset0:99 offset1:107
	ds_read2_b32 v[14:15], v155 offset0:132 offset1:140
	ds_read2_b32 v[16:17], v155 offset0:165 offset1:173
	ds_read2_b32 v[18:19], v155 offset0:198 offset1:206
	ds_read2_b32 v[20:21], v155 offset0:231 offset1:239
	s_or_b32 s8, s8, s9
	v_or_b32_e32 v24, s8, v140
	s_ashr_i32 s27, s26, 31
	v_ashrrev_i32_e32 v25, 31, v24
	v_lshl_add_u64 v[22:23], s[26:27], 1, v[50:51]
	v_lshlrev_b64 v[24:25], 11, v[24:25]
	s_waitcnt lgkmcnt(6)
	v_cvt_pk_bf16_f32 v2, v8, v6
	s_waitcnt lgkmcnt(4)
	v_cvt_pk_bf16_f32 v3, v10, v12
	s_waitcnt lgkmcnt(2)
	v_cvt_pk_bf16_f32 v4, v14, v16
	s_waitcnt lgkmcnt(0)
	v_cvt_pk_bf16_f32 v5, v18, v20
	v_lshl_add_u64 v[24:25], v[22:23], 0, v[24:25]
	v_or_b32_e32 v6, s8, v142
	global_store_dwordx4 v[24:25], v[2:5], off sc1
	s_nop 1
	v_cvt_pk_bf16_f32 v2, v9, v7
	v_ashrrev_i32_e32 v7, 31, v6
	v_cvt_pk_bf16_f32 v3, v11, v13
	v_cvt_pk_bf16_f32 v4, v15, v17
	v_cvt_pk_bf16_f32 v5, v19, v21
	v_lshlrev_b64 v[6:7], 11, v[6:7]
	ds_read2_b32 v[8:9], v155 offset0:49 offset1:57
	ds_read2_b32 v[10:11], v155 offset0:16 offset1:24
	ds_read2_b32 v[12:13], v155 offset0:82 offset1:90
	ds_read2_b32 v[14:15], v155 offset0:115 offset1:123
	ds_read2_b32 v[16:17], v155 offset0:148 offset1:156
	ds_read2_b32 v[18:19], v155 offset0:181 offset1:189
	ds_read2_b32 v[20:21], v155 offset0:214 offset1:222
	ds_read2_b32 v[24:25], v155 offset0:247 offset1:255
	v_lshl_add_u64 v[6:7], v[22:23], 0, v[6:7]
	global_store_dwordx4 v[6:7], v[2:5], off sc1
	v_or_b32_e32 v6, s8, v143
	v_ashrrev_i32_e32 v7, 31, v6
	v_lshlrev_b64 v[6:7], 11, v[6:7]
	s_waitcnt lgkmcnt(6)
	v_cvt_pk_bf16_f32 v2, v10, v8
	s_waitcnt lgkmcnt(4)
	v_cvt_pk_bf16_f32 v3, v12, v14
	s_waitcnt lgkmcnt(2)
	v_cvt_pk_bf16_f32 v4, v16, v18
	s_waitcnt lgkmcnt(0)
	v_cvt_pk_bf16_f32 v5, v20, v24
	v_lshl_add_u64 v[6:7], v[22:23], 0, v[6:7]
	global_store_dwordx4 v[6:7], v[2:5], off sc1
	v_or_b32_e32 v6, s8, v144
	v_ashrrev_i32_e32 v7, 31, v6
	v_lshlrev_b64 v[6:7], 11, v[6:7]
	v_cvt_pk_bf16_f32 v2, v11, v9
	v_cvt_pk_bf16_f32 v3, v13, v15
	v_cvt_pk_bf16_f32 v4, v17, v19
	v_cvt_pk_bf16_f32 v5, v21, v25
	v_lshl_add_u64 v[6:7], v[22:23], 0, v[6:7]
	global_store_dwordx4 v[6:7], v[2:5], off sc1
	s_waitcnt lgkmcnt(0)

; #define LAS __attribute__((address_space(3)))
; __device__ __forceinline__ unsigned pk2(float lo, float hi) { f32x2 v = {lo, hi}; bf2_t b = __builtin_convertvector(v, bf2_t); return __builtin_bit_cast(unsigned, b); }
;     ...
;       for (int i = 0; i < 8; ++i) { const int kk = 8 * i + (lane >> 3); LAS float* d = scr + kk * 33 + 4 * (lane & 7); d[0] = wv[i][0] * gv[i]; d[1] = wv[i][1] * gv[i]; d[2] = wv[i][2] * gv[i]; d[3] = wv[i][3] * gv[i]; } }
;     asm volatile("s_waitcnt lgkmcnt(0)" ::: "memory");
;     const int c = lane & 7; const int r0 = dst_row(dmode, n0);
; #pragma unroll
;     for (int j = 0; j < 4; ++j) { const int n = (lane >> 3) + 8 * j; const LAS float* s = scr + (8 * c) * 33 + n;
;         u32x4 o; o.x = pk2(s[0 * 33], s[1 * 33]); o.y = pk2(s[2 * 33], s[3 * 33]); o.z = pk2(s[4 * 33], s[5 * 33]); o.w = pk2(s[6 * 33], s[7 * 33]);
;         *(u32x4*)(WT + (size_t)(r0 + n) * pitch + k0 + 8 * c) = o; }
.LBB0_35:
	s_waitcnt vmcnt(7)
	v_pk_mul_f32 v[2:3], v[2:3], v[126:127] op_sel_hi:[1,0]
	v_add_u32_e32 v34, v105, v141
	ds_write2_b32 v34, v2, v3 offset1:1
	v_pk_mul_f32 v[2:3], v[4:5], v[126:127] op_sel_hi:[1,0]
	ds_write2_b32 v34, v2, v3 offset0:2 offset1:3
	s_waitcnt vmcnt(6)
	v_pk_mul_f32 v[2:3], v[6:7], v[124:125] op_sel_hi:[1,0]
	v_add_u32_e32 v4, 0x420, v34
	ds_write2_b32 v4, v2, v3 offset1:1
	v_pk_mul_f32 v[2:3], v[8:9], v[124:125] op_sel_hi:[1,0]
	v_add_u32_e32 v4, 0x428, v34
	ds_write2_b32 v4, v2, v3 offset1:1
	s_waitcnt vmcnt(5)
	v_pk_mul_f32 v[2:3], v[10:11], v[130:131] op_sel_hi:[1,0]
	v_add_u32_e32 v4, 0x840, v34
	ds_write2_b32 v4, v2, v3 offset1:1
	v_pk_mul_f32 v[2:3], v[12:13], v[130:131] op_sel_hi:[1,0]
	v_add_u32_e32 v4, 0x848, v34
	ds_write2_b32 v4, v2, v3 offset1:1
	s_waitcnt vmcnt(4)
	v_pk_mul_f32 v[2:3], v[14:15], v[128:129] op_sel_hi:[1,0]
	v_add_u32_e32 v4, 0xc60, v34
	ds_write2_b32 v4, v2, v3 offset1:1
	v_pk_mul_f32 v[2:3], v[16:17], v[128:129] op_sel_hi:[1,0]
	v_add_u32_e32 v4, 0xc68, v34
	ds_write2_b32 v4, v2, v3 offset1:1
	s_waitcnt vmcnt(3)
	v_pk_mul_f32 v[2:3], v[18:19], v[136:137] op_sel_hi:[1,0]
	v_add_u32_e32 v4, 0x1080, v34
	ds_write2_b32 v4, v2, v3 offset1:1
	v_pk_mul_f32 v[2:3], v[20:21], v[136:137] op_sel_hi:[1,0]
	v_add_u32_e32 v4, 0x1088, v34
	ds_write2_b32 v4, v2, v3 offset1:1
	s_waitcnt vmcnt(2)
	v_pk_mul_f32 v[2:3], v[22:23], v[132:133] op_sel_hi:[1,0]
	v_add_u32_e32 v4, 0x14a0, v34
	ds_write2_b32 v4, v2, v3 offset1:1
	v_pk_mul_f32 v[2:3], v[24:25], v[132:133] op_sel_hi:[1,0]
	v_add_u32_e32 v4, 0x14a8, v34
	ds_write2_b32 v4, v2, v3 offset1:1
	s_waitcnt vmcnt(1)
	v_pk_mul_f32 v[2:3], v[26:27], v[138:139] op_sel_hi:[1,0]
	v_add_u32_e32 v4, 0x18c0, v34
	ds_write2_b32 v4, v2, v3 offset1:1
	v_pk_mul_f32 v[2:3], v[28:29], v[138:139] op_sel_hi:[1,0]
	v_add_u32_e32 v4, 0x18c8, v34
	ds_write2_b32 v4, v2, v3 offset1:1
	s_waitcnt vmcnt(0)
	v_pk_mul_f32 v[2:3], v[30:31], v[134:135] op_sel_hi:[1,0]
	v_add_u32_e32 v4, 0x1ce0, v34
	ds_write2_b32 v4, v2, v3 offset1:1
	v_pk_mul_f32 v[2:3], v[32:33], v[134:135] op_sel_hi:[1,0]
	v_add_u32_e32 v4, 0x1ce8, v34
	ds_write2_b32 v4, v2, v3 offset1:1
	s_waitcnt lgkmcnt(0)
	s_and_b32 s8, s8, 0xf00
	s_and_b32 s9, s22, 0x80
	s_or_b32 s8, s9, s8
	s_lshl_b32 s9, s27, 4
	ds_read2_b32 v[6:7], v155 offset0:33 offset1:41
	ds_read2_b32 v[8:9], v155 offset1:8
	ds_read2_b32 v[10:11], v155 offset0:66 offset1:74
	ds_read2_b32 v[12:13], v155 offset0:99 offset1:107
	ds_read2_b32 v[14:15], v155 offset0:132 offset1:140
	ds_read2_b32 v[16:17], v155 offset0:165 offset1:173
	ds_read2_b32 v[18:19], v155 offset0:198 offset1:206
	ds_read2_b32 v[20:21], v155 offset0:231 offset1:239
	s_and_b32 s9, s9, 0x60
	s_or_b32 s8, s8, s9
	s_lshl_b32 s22, s26, 1
	s_waitcnt lgkmcnt(6)
	v_cvt_pk_bf16_f32 v2, v8, v6
	v_or_b32_e32 v6, s8, v140
	v_lshl_add_u64 v[22:23], v[38:39], 0, s[22:23]
	v_lshlrev_b32_e32 v34, 11, v6
	s_waitcnt lgkmcnt(4)
	v_cvt_pk_bf16_f32 v3, v10, v12
	s_waitcnt lgkmcnt(2)
	v_cvt_pk_bf16_f32 v4, v14, v16
	s_waitcnt lgkmcnt(0)
	v_cvt_pk_bf16_f32 v5, v18, v20
	v_lshl_add_u64 v[24:25], v[22:23], 0, v[34:35]
	global_store_dwordx4 v[24:25], v[2:5], off sc1
	v_or_b32_e32 v6, s8, v142
	v_lshlrev_b32_e32 v34, 11, v6
	v_cvt_pk_bf16_f32 v2, v9, v7
	v_cvt_pk_bf16_f32 v3, v11, v13
	v_cvt_pk_bf16_f32 v4, v15, v17
	v_cvt_pk_bf16_f32 v5, v19, v21
	ds_read2_b32 v[8:9], v155 offset0:49 offset1:57
	ds_read2_b32 v[10:11], v155 offset0:16 offset1:24
	ds_read2_b32 v[12:13], v155 offset0:82 offset1:90
	ds_read2_b32 v[14:15], v155 offset0:115 offset1:123
	ds_read2_b32 v[16:17], v155 offset0:148 offset1:156
	ds_read2_b32 v[18:19], v155 offset0:181 offset1:189
	ds_read2_b32 v[20:21], v155 offset0:214 offset1:222
	ds_read2_b32 v[24:25], v155 offset0:247 offset1:255
	v_lshl_add_u64 v[6:7], v[22:23], 0, v[34:35]
	global_store_dwordx4 v[6:7], v[2:5], off sc1
	v_or_b32_e32 v6, s8, v143
	v_lshlrev_b32_e32 v34, 11, v6
	s_waitcnt lgkmcnt(6)
	v_cvt_pk_bf16_f32 v2, v10, v8
	s_waitcnt lgkmcnt(4)
	v_cvt_pk_bf16_f32 v3, v12, v14
	s_waitcnt lgkmcnt(2)
	v_cvt_pk_bf16_f32 v4, v16, v18
	s_waitcnt lgkmcnt(0)
	v_cvt_pk_bf16_f32 v5, v20, v24
	v_lshl_add_u64 v[6:7], v[22:23], 0, v[34:35]
	global_store_dwordx4 v[6:7], v[2:5], off sc1
	v_or_b32_e32 v6, s8, v144
	v_lshlrev_b32_e32 v34, 11, v6
	v_cvt_pk_bf16_f32 v2, v11, v9
	v_cvt_pk_bf16_f32 v3, v13, v15
	v_cvt_pk_bf16_f32 v4, v17, v19
	v_cvt_pk_bf16_f32 v5, v21, v25
	v_lshl_add_u64 v[6:7], v[22:23], 0, v[34:35]
	global_store_dwordx4 v[6:7], v[2:5], off sc1
	s_waitcnt lgkmcnt(0)
	s_mov_b64 s[8:9], 0
; #define LAS __attribute__((address_space(3)))
; __device__ __forceinline__ unsigned pk2(float lo, float hi) { f32x2 v = {lo, hi}; bf2_t b = __builtin_convertvector(v, bf2_t); return __builtin_bit_cast(unsigned, b); }
;     ...
;       for (int i = 0; i < 8; ++i) { const int kk = 8 * i + (lane >> 3); wv[i] = *(const f32x4*)(W + (size_t)(k0 + kk) * N + n0 + 4 * (lane & 7)); gv[i] = gain ? gain[k0 + kk] : 1.0f; }
; #pragma unroll
;       for (int i = 0; i < 8; ++i) { const int kk = 8 * i + (lane >> 3); LAS float* d = scr + kk * 33 + 4 * (lane & 7); d[0] = wv[i][0] * gv[i]; d[1] = wv[i][1] * gv[i]; d[2] = wv[i][2] * gv[i]; d[3] = wv[i][3] * gv[i]; } }
;     asm volatile("s_waitcnt lgkmcnt(0)" ::: "memory");
;     const int c = lane & 7; const int r0 = dst_row(dmode, n0);
; #pragma unroll
;     for (int j = 0; j < 4; ++j) { const int n = (lane >> 3) + 8 * j; const LAS float* s = scr + (8 * c) * 33 + n;
;         u32x4 o; o.x = pk2(s[0 * 33], s[1 * 33]); o.y = pk2(s[2 * 33], s[3 * 33]); o.z = pk2(s[4 * 33], s[5 * 33]); o.w = pk2(s[6 * 33], s[7 * 33]);
;         *(u32x4*)(WT + (size_t)(r0 + n) * pitch + k0 + 8 * c) = o; }
.LBB0_36:
	s_and_b64 vcc, exec, s[8:9]
	s_cbranch_vccz .LBB0_38
	s_and_b32 s9, s94, 0x1ffc0
	s_and_b32 s8, s78, 0x3e0
	s_waitcnt lgkmcnt(3)
	v_or_b32_e32 v4, s9, v140
	s_lshl_b32 s22, s8, 2
	v_lshl_add_u64 v[2:3], v[40:41], 0, s[22:23]
	v_lshlrev_b32_e32 v34, 12, v4
	v_lshl_add_u64 v[30:31], v[2:3], 0, v[34:35]
	s_waitcnt lgkmcnt(2)
	v_add_co_u32_e32 v6, vcc, 0x8000, v30
	v_add_u32_e32 v124, v105, v141
	s_nop 0
	v_addc_co_u32_e32 v7, vcc, 0, v31, vcc
	v_add_co_u32_e32 v10, vcc, 0x10000, v30
	global_load_dwordx4 v[2:5], v[30:31], off
	s_waitcnt lgkmcnt(0)
	global_load_dwordx4 v[6:9], v[6:7], off
	v_addc_co_u32_e32 v11, vcc, 0, v31, vcc
	v_add_co_u32_e32 v14, vcc, 0x18000, v30
	v_add_u32_e32 v126, 0x420, v124
	s_nop 0
	v_addc_co_u32_e32 v15, vcc, 0, v31, vcc
	v_add_co_u32_e32 v18, vcc, s71, v30
	global_load_dwordx4 v[10:13], v[10:11], off
	s_nop 0
	global_load_dwordx4 v[14:17], v[14:15], off
	v_addc_co_u32_e32 v19, vcc, 0, v31, vcc
	v_add_co_u32_e32 v22, vcc, 0x28000, v30
	v_add_u32_e32 v128, 0x428, v124
	s_nop 0
	v_addc_co_u32_e32 v23, vcc, 0, v31, vcc
	global_load_dwordx4 v[18:21], v[18:19], off
	s_nop 0
	global_load_dwordx4 v[22:25], v[22:23], off
	v_add_co_u32_e32 v26, vcc, 0x30000, v30
	v_add_u32_e32 v132, 0x840, v124
	s_nop 0
	v_addc_co_u32_e32 v27, vcc, 0, v31, vcc
	global_load_dwordx4 v[26:29], v[26:27], off
	v_add_co_u32_e32 v30, vcc, 0x38000, v30
	v_add_u32_e32 v134, 0x848, v124
	s_nop 0
	v_addc_co_u32_e32 v31, vcc, 0, v31, vcc
	global_load_dwordx4 v[30:33], v[30:31], off
	v_add_u32_e32 v136, 0xc60, v124
	v_add_u32_e32 v138, 0xc68, v124
	v_add_u32_e32 v156, 0x1080, v124
	v_add_u32_e32 v157, 0x1088, v124
	v_add_u32_e32 v158, 0x14a0, v124
	v_add_u32_e32 v159, 0x14a8, v124
	v_add_u32_e32 v160, 0x18c0, v124
	v_add_u32_e32 v161, 0x18c8, v124
	v_add_u32_e32 v162, 0x1ce0, v124
	v_add_u32_e32 v163, 0x1ce8, v124
	v_or_b32_e32 v34, s8, v140
	s_lshl_b32 s22, s9, 1
	v_mul_u32_u24_e32 v34, 0xb00, v34
	v_lshl_add_u64 v[130:131], v[42:43], 0, s[22:23]
	v_lshlrev_b32_e32 v34, 1, v34
	s_waitcnt vmcnt(7)
	ds_write2_b32 v124, v2, v3 offset1:1
	ds_write2_b32 v124, v4, v5 offset0:2 offset1:3
	s_waitcnt vmcnt(6)
	ds_write2_b32 v126, v6, v7 offset1:1
	ds_write2_b32 v128, v8, v9 offset1:1
	s_waitcnt vmcnt(5)
	ds_write2_b32 v132, v10, v11 offset1:1
	ds_write2_b32 v134, v12, v13 offset1:1
	s_waitcnt vmcnt(4)
	ds_write2_b32 v136, v14, v15 offset1:1
	ds_write2_b32 v138, v16, v17 offset1:1
	s_waitcnt vmcnt(3)
	ds_write2_b32 v156, v18, v19 offset1:1
	ds_write2_b32 v157, v20, v21 offset1:1
	s_waitcnt vmcnt(2)
	ds_write2_b32 v158, v22, v23 offset1:1
	ds_write2_b32 v159, v24, v25 offset1:1
	s_waitcnt vmcnt(1)
	ds_write2_b32 v160, v26, v27 offset1:1
	ds_write2_b32 v161, v28, v29 offset1:1
	s_waitcnt vmcnt(0)
	ds_write2_b32 v162, v30, v31 offset1:1
	ds_write2_b32 v163, v32, v33 offset1:1
	s_waitcnt lgkmcnt(0)
	ds_read2_b32 v[6:7], v155 offset0:33 offset1:41
	ds_read2_b32 v[8:9], v155 offset1:8
	ds_read2_b32 v[10:11], v155 offset0:66 offset1:74
	ds_read2_b32 v[12:13], v155 offset0:99 offset1:107
	ds_read2_b32 v[14:15], v155 offset0:132 offset1:140
	ds_read2_b32 v[16:17], v155 offset0:165 offset1:173
	ds_read2_b32 v[18:19], v155 offset0:198 offset1:206
	ds_read2_b32 v[20:21], v155 offset0:231 offset1:239
	v_lshl_add_u64 v[22:23], v[130:131], 0, v[34:35]
	s_waitcnt lgkmcnt(6)
	v_cvt_pk_bf16_f32 v2, v8, v6
	s_waitcnt lgkmcnt(4)
	v_cvt_pk_bf16_f32 v3, v10, v12
	s_waitcnt lgkmcnt(2)
	v_cvt_pk_bf16_f32 v4, v14, v16
	s_waitcnt lgkmcnt(0)
	v_cvt_pk_bf16_f32 v5, v18, v20
	global_store_dwordx4 v[22:23], v[2:5], off sc1
	v_cvt_pk_bf16_f32 v6, v9, v7
	v_cvt_pk_bf16_f32 v7, v11, v13
	v_or_b32_e32 v2, s8, v142
	v_mul_u32_u24_e32 v2, 0xb00, v2
	v_cvt_pk_bf16_f32 v8, v15, v17
	v_cvt_pk_bf16_f32 v9, v19, v21
	v_lshlrev_b32_e32 v34, 1, v2
	ds_read2_b32 v[10:11], v155 offset0:16 offset1:24
	ds_read2_b32 v[12:13], v155 offset0:49 offset1:57
	ds_read2_b32 v[14:15], v155 offset0:82 offset1:90
	ds_read2_b32 v[16:17], v155 offset0:115 offset1:123
	ds_read2_b32 v[18:19], v155 offset0:148 offset1:156
	ds_read2_b32 v[20:21], v155 offset0:181 offset1:189
	ds_read2_b32 v[22:23], v155 offset0:214 offset1:222
	ds_read2_b32 v[24:25], v155 offset0:247 offset1:255
	v_lshl_add_u64 v[2:3], v[130:131], 0, v[34:35]
	global_store_dwordx4 v[2:3], v[6:9], off sc1
	s_waitcnt lgkmcnt(6)
	v_cvt_pk_bf16_f32 v2, v10, v12
	s_waitcnt lgkmcnt(4)
	v_cvt_pk_bf16_f32 v3, v14, v16
	v_or_b32_e32 v6, s8, v143
	v_mul_u32_u24_e32 v6, 0xb00, v6
	v_lshlrev_b32_e32 v34, 1, v6
	s_waitcnt lgkmcnt(2)
	v_cvt_pk_bf16_f32 v4, v18, v20
	s_waitcnt lgkmcnt(0)
	v_cvt_pk_bf16_f32 v5, v22, v24
	v_lshl_add_u64 v[6:7], v[130:131], 0, v[34:35]
	global_store_dwordx4 v[6:7], v[2:5], off sc1
	v_or_b32_e32 v6, s8, v144
	v_mul_u32_u24_e32 v6, 0xb00, v6
	v_lshlrev_b32_e32 v34, 1, v6
	v_cvt_pk_bf16_f32 v2, v11, v13
	v_cvt_pk_bf16_f32 v3, v15, v17
	v_cvt_pk_bf16_f32 v4, v19, v21
	v_cvt_pk_bf16_f32 v5, v23, v25
	v_lshl_add_u64 v[6:7], v[130:131], 0, v[34:35]
	global_store_dwordx4 v[6:7], v[2:5], off sc1
	s_waitcnt lgkmcnt(0)

; #define LAS __attribute__((address_space(3)))
; __device__ __forceinline__ unsigned pk2(float lo, float hi) { f32x2 v = {lo, hi}; bf2_t b = __builtin_convertvector(v, bf2_t); return __builtin_bit_cast(unsigned, b); }
;     ...
;       for (int i = 0; i < 8; ++i) { const int kk = 8 * i + (lane >> 3); wv[i] = *(const f32x4*)(W + (size_t)(k0 + kk) * N + n0 + 4 * (lane & 7)); gv[i] = gain ? gain[k0 + kk] : 1.0f; }
; #pragma unroll
;       for (int i = 0; i < 8; ++i) { const int kk = 8 * i + (lane >> 3); LAS float* d = scr + kk * 33 + 4 * (lane & 7); d[0] = wv[i][0] * gv[i]; d[1] = wv[i][1] * gv[i]; d[2] = wv[i][2] * gv[i]; d[3] = wv[i][3] * gv[i]; } }
;     asm volatile("s_waitcnt lgkmcnt(0)" ::: "memory");
;     const int c = lane & 7; const int r0 = dst_row(dmode, n0);
; #pragma unroll
;     for (int j = 0; j < 4; ++j) { const int n = (lane >> 3) + 8 * j; const LAS float* s = scr + (8 * c) * 33 + n;
;         u32x4 o; o.x = pk2(s[0 * 33], s[1 * 33]); o.y = pk2(s[2 * 33], s[3 * 33]); o.z = pk2(s[4 * 33], s[5 * 33]); o.w = pk2(s[6 * 33], s[7 * 33]);
;         *(u32x4*)(WT + (size_t)(r0 + n) * pitch + k0 + 8 * c) = o; }
.LBB0_39:
	s_andn2_b64 vcc, exec, s[8:9]
	s_cbranch_vccnz .LBB0_41
	s_and_b32 s8, s96, 0x3c0
	s_and_b32 s9, s78, 0x1e0
	s_waitcnt lgkmcnt(3)
	v_or_b32_e32 v4, s8, v140
	s_lshl_b32 s22, s9, 2
	v_lshl_add_u64 v[2:3], v[44:45], 0, s[22:23]
	v_lshlrev_b32_e32 v34, 11, v4
	v_lshl_add_u64 v[30:31], v[2:3], 0, v[34:35]
	s_waitcnt lgkmcnt(2)
	v_add_co_u32_e32 v6, vcc, 0x4000, v30
	s_mov_b32 s9, 0x8000
	s_nop 0
	v_addc_co_u32_e32 v7, vcc, 0, v31, vcc
	v_add_co_u32_e32 v10, vcc, s9, v30
	s_mov_b32 s9, 0x10000
	s_nop 0
	v_addc_co_u32_e32 v11, vcc, 0, v31, vcc
	v_add_co_u32_e32 v14, vcc, 0xc000, v30
	global_load_dwordx4 v[2:5], v[30:31], off
	s_waitcnt lgkmcnt(0)
	global_load_dwordx4 v[6:9], v[6:7], off
	v_addc_co_u32_e32 v15, vcc, 0, v31, vcc
	v_add_co_u32_e32 v18, vcc, s9, v30
	global_load_dwordx4 v[10:13], v[10:11], off
	s_nop 0
	global_load_dwordx4 v[14:17], v[14:15], off
	v_addc_co_u32_e32 v19, vcc, 0, v31, vcc
	v_add_co_u32_e32 v22, vcc, 0x14000, v30
	s_mov_b32 s9, 0x18000
	s_nop 0
	v_addc_co_u32_e32 v23, vcc, 0, v31, vcc
	global_load_dwordx4 v[18:21], v[18:19], off
	s_nop 0
	global_load_dwordx4 v[22:25], v[22:23], off
	v_add_co_u32_e32 v26, vcc, s9, v30
	v_add_u32_e32 v34, v105, v141
	s_nop 0
	v_addc_co_u32_e32 v27, vcc, 0, v31, vcc
	global_load_dwordx4 v[26:29], v[26:27], off
	v_add_co_u32_e32 v30, vcc, 0x1c000, v30
	v_add_u32_e32 v124, 0x420, v34
	s_nop 0
	v_addc_co_u32_e32 v31, vcc, 0, v31, vcc
	global_load_dwordx4 v[30:33], v[30:31], off
	v_add_u32_e32 v126, 0x428, v34
	v_add_u32_e32 v128, 0x840, v34
	v_add_u32_e32 v130, 0x848, v34
	v_add_u32_e32 v131, 0xc60, v34
	v_add_u32_e32 v132, 0xc68, v34
	v_add_u32_e32 v134, 0x1080, v34
	v_add_u32_e32 v136, 0x1088, v34
	v_add_u32_e32 v138, 0x14a0, v34
	v_add_u32_e32 v156, 0x14a8, v34
	v_add_u32_e32 v157, 0x18c0, v34
	v_add_u32_e32 v158, 0x18c8, v34
	v_add_u32_e32 v159, 0x1ce0, v34
	v_add_u32_e32 v160, 0x1ce8, v34
	s_and_b32 s9, s78, 0x100
	s_and_b32 s22, s80, 0x80
	s_and_b32 s26, s63, 0x60
	s_or_b32 s9, s22, s9
	s_or_b32 s9, s9, s26
	s_lshl_b32 s22, s8, 1
	s_waitcnt vmcnt(7)
	ds_write2_b32 v34, v2, v3 offset1:1
	ds_write2_b32 v34, v4, v5 offset0:2 offset1:3
	s_waitcnt vmcnt(6)
	ds_write2_b32 v124, v6, v7 offset1:1
	ds_write2_b32 v126, v8, v9 offset1:1
	s_waitcnt vmcnt(5)
	ds_write2_b32 v128, v10, v11 offset1:1
	ds_write2_b32 v130, v12, v13 offset1:1
	s_waitcnt vmcnt(4)
	ds_write2_b32 v131, v14, v15 offset1:1
	ds_write2_b32 v132, v16, v17 offset1:1
	s_waitcnt vmcnt(3)
	ds_write2_b32 v134, v18, v19 offset1:1
	ds_write2_b32 v136, v20, v21 offset1:1
	s_waitcnt vmcnt(2)
	ds_write2_b32 v138, v22, v23 offset1:1
	ds_write2_b32 v156, v24, v25 offset1:1
	s_waitcnt vmcnt(1)
	ds_write2_b32 v157, v26, v27 offset1:1
	ds_write2_b32 v158, v28, v29 offset1:1
	s_waitcnt vmcnt(0)
	ds_write2_b32 v159, v30, v31 offset1:1
	ds_write2_b32 v160, v32, v33 offset1:1
	s_waitcnt lgkmcnt(0)
	ds_read2_b32 v[6:7], v155 offset0:33 offset1:41
	ds_read2_b32 v[8:9], v155 offset1:8
	ds_read2_b32 v[10:11], v155 offset0:66 offset1:74
	ds_read2_b32 v[12:13], v155 offset0:99 offset1:107
	ds_read2_b32 v[14:15], v155 offset0:132 offset1:140
	ds_read2_b32 v[16:17], v155 offset0:165 offset1:173
	ds_read2_b32 v[18:19], v155 offset0:198 offset1:206
	ds_read2_b32 v[20:21], v155 offset0:231 offset1:239
	s_waitcnt lgkmcnt(6)
	v_cvt_pk_bf16_f32 v2, v8, v6
	v_or_b32_e32 v6, s9, v140
	v_lshl_add_u64 v[22:23], v[46:47], 0, s[22:23]
	v_lshlrev_b32_e32 v34, 11, v6
	s_waitcnt lgkmcnt(4)
	v_cvt_pk_bf16_f32 v3, v10, v12
	s_waitcnt lgkmcnt(2)
	v_cvt_pk_bf16_f32 v4, v14, v16
	s_waitcnt lgkmcnt(0)
	v_cvt_pk_bf16_f32 v5, v18, v20
	v_lshl_add_u64 v[24:25], v[22:23], 0, v[34:35]
	global_store_dwordx4 v[24:25], v[2:5], off sc1
	v_or_b32_e32 v6, s9, v142
	v_lshlrev_b32_e32 v34, 11, v6
	v_cvt_pk_bf16_f32 v2, v9, v7
	v_cvt_pk_bf16_f32 v3, v11, v13
	v_cvt_pk_bf16_f32 v4, v15, v17
	v_cvt_pk_bf16_f32 v5, v19, v21
	ds_read2_b32 v[8:9], v155 offset0:49 offset1:57
	ds_read2_b32 v[10:11], v155 offset0:16 offset1:24
	ds_read2_b32 v[12:13], v155 offset0:82 offset1:90
	ds_read2_b32 v[14:15], v155 offset0:115 offset1:123
	ds_read2_b32 v[16:17], v155 offset0:148 offset1:156
	ds_read2_b32 v[18:19], v155 offset0:181 offset1:189
	ds_read2_b32 v[20:21], v155 offset0:214 offset1:222
	ds_read2_b32 v[24:25], v155 offset0:247 offset1:255
	v_lshl_add_u64 v[6:7], v[22:23], 0, v[34:35]
	global_store_dwordx4 v[6:7], v[2:5], off sc1
	v_or_b32_e32 v6, s9, v143
	v_lshlrev_b32_e32 v34, 11, v6
	s_waitcnt lgkmcnt(6)
	v_cvt_pk_bf16_f32 v2, v10, v8
	s_waitcnt lgkmcnt(4)
	v_cvt_pk_bf16_f32 v3, v12, v14
	s_waitcnt lgkmcnt(2)
	v_cvt_pk_bf16_f32 v4, v16, v18
	s_waitcnt lgkmcnt(0)
	v_cvt_pk_bf16_f32 v5, v20, v24
	v_lshl_add_u64 v[6:7], v[22:23], 0, v[34:35]
	global_store_dwordx4 v[6:7], v[2:5], off sc1
	v_or_b32_e32 v6, s9, v144
	v_lshlrev_b32_e32 v34, 11, v6
	v_cvt_pk_bf16_f32 v2, v11, v9
	v_cvt_pk_bf16_f32 v3, v13, v15
	v_cvt_pk_bf16_f32 v4, v17, v19
	v_cvt_pk_bf16_f32 v5, v21, v25
	v_lshl_add_u64 v[6:7], v[22:23], 0, v[34:35]
	global_store_dwordx4 v[6:7], v[2:5], off sc1
	s_waitcnt lgkmcnt(0)

; #define LAS __attribute__((address_space(3)))
; __device__ __forceinline__ unsigned pk2(float lo, float hi) { f32x2 v = {lo, hi}; bf2_t b = __builtin_convertvector(v, bf2_t); return __builtin_bit_cast(unsigned, b); }
;     ...
;       for (int i = 0; i < 8; ++i) { const int kk = 8 * i + (lane >> 3); LAS float* d = scr + kk * 33 + 4 * (lane & 7); d[0] = wv[i][0] * gv[i]; d[1] = wv[i][1] * gv[i]; d[2] = wv[i][2] * gv[i]; d[3] = wv[i][3] * gv[i]; } }
;     asm volatile("s_waitcnt lgkmcnt(0)" ::: "memory");
;     const int c = lane & 7; const int r0 = dst_row(dmode, n0);
; #pragma unroll
;     for (int j = 0; j < 4; ++j) { const int n = (lane >> 3) + 8 * j; const LAS float* s = scr + (8 * c) * 33 + n;
;         u32x4 o; o.x = pk2(s[0 * 33], s[1 * 33]); o.y = pk2(s[2 * 33], s[3 * 33]); o.z = pk2(s[4 * 33], s[5 * 33]); o.w = pk2(s[6 * 33], s[7 * 33]);
;         *(u32x4*)(WT + (size_t)(r0 + n) * pitch + k0 + 8 * c) = o; }
.LBB0_59:
	s_waitcnt vmcnt(7)
	v_pk_mul_f32 v[2:3], v[2:3], v[126:127] op_sel_hi:[1,0]
	v_add_u32_e32 v131, v105, v141
	ds_write2_b32 v131, v2, v3 offset1:1
	v_pk_mul_f32 v[2:3], v[4:5], v[126:127] op_sel_hi:[1,0]
	ds_write2_b32 v131, v2, v3 offset0:2 offset1:3
	s_waitcnt vmcnt(6)
	v_pk_mul_f32 v[2:3], v[6:7], v[34:35] op_sel_hi:[1,0]
	v_add_u32_e32 v4, 0x420, v131
	ds_write2_b32 v4, v2, v3 offset1:1
	v_pk_mul_f32 v[2:3], v[8:9], v[34:35] op_sel_hi:[1,0]
	v_add_u32_e32 v4, 0x428, v131
	ds_write2_b32 v4, v2, v3 offset1:1
	s_waitcnt vmcnt(5)
	v_pk_mul_f32 v[2:3], v[10:11], v[130:131] op_sel_hi:[1,0]
	v_add_u32_e32 v4, 0x840, v131
	ds_write2_b32 v4, v2, v3 offset1:1
	v_pk_mul_f32 v[2:3], v[12:13], v[130:131] op_sel_hi:[1,0]
	v_add_u32_e32 v4, 0x848, v131
	ds_write2_b32 v4, v2, v3 offset1:1
	s_waitcnt vmcnt(4)
	v_pk_mul_f32 v[2:3], v[14:15], v[124:125] op_sel_hi:[1,0]
	v_add_u32_e32 v4, 0xc60, v131
	ds_write2_b32 v4, v2, v3 offset1:1
	v_pk_mul_f32 v[2:3], v[16:17], v[124:125] op_sel_hi:[1,0]
	v_add_u32_e32 v4, 0xc68, v131
	ds_write2_b32 v4, v2, v3 offset1:1
	s_waitcnt vmcnt(3)
	v_pk_mul_f32 v[2:3], v[18:19], v[134:135] op_sel_hi:[1,0]
	v_add_u32_e32 v4, 0x1080, v131
	ds_write2_b32 v4, v2, v3 offset1:1
	v_pk_mul_f32 v[2:3], v[20:21], v[134:135] op_sel_hi:[1,0]
	v_add_u32_e32 v4, 0x1088, v131
	ds_write2_b32 v4, v2, v3 offset1:1
	s_waitcnt vmcnt(2)
	v_pk_mul_f32 v[2:3], v[22:23], v[128:129] op_sel_hi:[1,0]
	v_add_u32_e32 v4, 0x14a0, v131
	ds_write2_b32 v4, v2, v3 offset1:1
	v_pk_mul_f32 v[2:3], v[24:25], v[128:129] op_sel_hi:[1,0]
	v_add_u32_e32 v4, 0x14a8, v131
	ds_write2_b32 v4, v2, v3 offset1:1
	s_waitcnt vmcnt(1)
	v_pk_mul_f32 v[2:3], v[26:27], v[136:137] op_sel_hi:[1,0]
	v_add_u32_e32 v4, 0x18c0, v131
	ds_write2_b32 v4, v2, v3 offset1:1
	v_pk_mul_f32 v[2:3], v[28:29], v[136:137] op_sel_hi:[1,0]
	v_add_u32_e32 v4, 0x18c8, v131
	ds_write2_b32 v4, v2, v3 offset1:1
	s_waitcnt vmcnt(0)
	v_pk_mul_f32 v[2:3], v[30:31], v[132:133] op_sel_hi:[1,0]
	v_add_u32_e32 v4, 0x1ce0, v131
	ds_write2_b32 v4, v2, v3 offset1:1
	v_pk_mul_f32 v[2:3], v[32:33], v[132:133] op_sel_hi:[1,0]
	v_add_u32_e32 v4, 0x1ce8, v131
	ds_write2_b32 v4, v2, v3 offset1:1
	s_waitcnt lgkmcnt(0)
	s_lshl_b32 s9, s27, 6
	s_and_b32 s9, s9, 0x1f00
	s_and_b32 s8, s8, 0x60
	ds_read2_b32 v[6:7], v155 offset0:33 offset1:41
	ds_read2_b32 v[8:9], v155 offset1:8
	ds_read2_b32 v[10:11], v155 offset0:66 offset1:74
	ds_read2_b32 v[12:13], v155 offset0:99 offset1:107
	ds_read2_b32 v[14:15], v155 offset0:132 offset1:140
	ds_read2_b32 v[16:17], v155 offset0:165 offset1:173
	ds_read2_b32 v[18:19], v155 offset0:198 offset1:206
	ds_read2_b32 v[20:21], v155 offset0:231 offset1:239
	s_or_b32 s8, s8, s9
	s_bitset1_b32 s8, 7
	s_and_b32 s9, 0xffff, s26
	s_lshl_b32 s22, s9, 1
	s_waitcnt lgkmcnt(6)
	v_cvt_pk_bf16_f32 v2, v8, v6
	v_or_b32_e32 v6, s8, v140
	v_lshl_add_u64 v[22:23], v[50:51], 0, s[22:23]
	v_lshlrev_b32_e32 v34, 11, v6
	s_waitcnt lgkmcnt(4)
	v_cvt_pk_bf16_f32 v3, v10, v12
	s_waitcnt lgkmcnt(2)
	v_cvt_pk_bf16_f32 v4, v14, v16
	s_waitcnt lgkmcnt(0)
	v_cvt_pk_bf16_f32 v5, v18, v20
	v_lshl_add_u64 v[24:25], v[22:23], 0, v[34:35]
	global_store_dwordx4 v[24:25], v[2:5], off sc1
	v_or_b32_e32 v6, s8, v142
	v_lshlrev_b32_e32 v34, 11, v6
	v_cvt_pk_bf16_f32 v2, v9, v7
	v_cvt_pk_bf16_f32 v3, v11, v13
	v_cvt_pk_bf16_f32 v4, v15, v17
	v_cvt_pk_bf16_f32 v5, v19, v21
	ds_read2_b32 v[8:9], v155 offset0:49 offset1:57
	ds_read2_b32 v[10:11], v155 offset0:16 offset1:24
	ds_read2_b32 v[12:13], v155 offset0:82 offset1:90
	ds_read2_b32 v[14:15], v155 offset0:115 offset1:123
	ds_read2_b32 v[16:17], v155 offset0:148 offset1:156
	ds_read2_b32 v[18:19], v155 offset0:181 offset1:189
	ds_read2_b32 v[20:21], v155 offset0:214 offset1:222
	ds_read2_b32 v[24:25], v155 offset0:247 offset1:255
	v_lshl_add_u64 v[6:7], v[22:23], 0, v[34:35]
	global_store_dwordx4 v[6:7], v[2:5], off sc1
	v_or_b32_e32 v6, s8, v143
	v_lshlrev_b32_e32 v34, 11, v6
	s_waitcnt lgkmcnt(6)
	v_cvt_pk_bf16_f32 v2, v10, v8
	s_waitcnt lgkmcnt(4)
	v_cvt_pk_bf16_f32 v3, v12, v14
	s_waitcnt lgkmcnt(2)
	v_cvt_pk_bf16_f32 v4, v16, v18
	s_waitcnt lgkmcnt(0)
	v_cvt_pk_bf16_f32 v5, v20, v24
	v_lshl_add_u64 v[6:7], v[22:23], 0, v[34:35]
	global_store_dwordx4 v[6:7], v[2:5], off sc1
	v_or_b32_e32 v6, s8, v144
	v_lshlrev_b32_e32 v34, 11, v6
	v_cvt_pk_bf16_f32 v2, v11, v9
	v_cvt_pk_bf16_f32 v3, v13, v15
	v_cvt_pk_bf16_f32 v4, v17, v19
	v_cvt_pk_bf16_f32 v5, v21, v25
	v_lshl_add_u64 v[6:7], v[22:23], 0, v[34:35]
	global_store_dwordx4 v[6:7], v[2:5], off sc1
	s_waitcnt lgkmcnt(0)

; #define LAS __attribute__((address_space(3)))
; __device__ __forceinline__ unsigned pk2(float lo, float hi) { f32x2 v = {lo, hi}; bf2_t b = __builtin_convertvector(v, bf2_t); return __builtin_bit_cast(unsigned, b); }
;     ...
;       for (int i = 0; i < 8; ++i) { const int kk = 8 * i + (lane >> 3); LAS float* d = scr + kk * 33 + 4 * (lane & 7); d[0] = wv[i][0] * gv[i]; d[1] = wv[i][1] * gv[i]; d[2] = wv[i][2] * gv[i]; d[3] = wv[i][3] * gv[i]; } }
;     asm volatile("s_waitcnt lgkmcnt(0)" ::: "memory");
;     const int c = lane & 7; const int r0 = dst_row(dmode, n0);
; #pragma unroll
;     for (int j = 0; j < 4; ++j) { const int n = (lane >> 3) + 8 * j; const LAS float* s = scr + (8 * c) * 33 + n;
;         u32x4 o; o.x = pk2(s[0 * 33], s[1 * 33]); o.y = pk2(s[2 * 33], s[3 * 33]); o.z = pk2(s[4 * 33], s[5 * 33]); o.w = pk2(s[6 * 33], s[7 * 33]);
;         *(u32x4*)(WT + (size_t)(r0 + n) * pitch + k0 + 8 * c) = o; }
; __device__ __forceinline__ void convert_item(const Args& a, int set, int it, LAS float* scr, int lane) {
;     ...
;     if (r < I_GT) { p0_transpose_item(a.in[I_WGATE], D, 3 * D, a.in[I_MIXN], (bf16_t*)(ws + WS_WG), 0, scr, r, lane); return; } r -= I_GT;
.LBB0_80:
	s_waitcnt vmcnt(7)
	v_pk_mul_f32 v[2:3], v[2:3], v[126:127] op_sel_hi:[1,0]
	v_add_u32_e32 v130, v105, v141
	ds_write2_b32 v130, v2, v3 offset1:1
	v_pk_mul_f32 v[2:3], v[4:5], v[126:127] op_sel_hi:[1,0]
	ds_write2_b32 v130, v2, v3 offset0:2 offset1:3
	s_waitcnt vmcnt(6)
	v_pk_mul_f32 v[2:3], v[6:7], v[34:35] op_sel_hi:[1,0]
	v_add_u32_e32 v4, 0x420, v130
	ds_write2_b32 v4, v2, v3 offset1:1
	v_pk_mul_f32 v[2:3], v[8:9], v[34:35] op_sel_hi:[1,0]
	v_add_u32_e32 v4, 0x428, v130
	ds_write2_b32 v4, v2, v3 offset1:1
	s_waitcnt vmcnt(5)
	v_pk_mul_f32 v[2:3], v[10:11], v[132:133] op_sel_hi:[1,0]
	v_add_u32_e32 v4, 0x840, v130
	ds_write2_b32 v4, v2, v3 offset1:1
	v_pk_mul_f32 v[2:3], v[12:13], v[132:133] op_sel_hi:[1,0]
	v_add_u32_e32 v4, 0x848, v130
	ds_write2_b32 v4, v2, v3 offset1:1
	s_waitcnt vmcnt(4)
	v_pk_mul_f32 v[2:3], v[14:15], v[124:125] op_sel_hi:[1,0]
	v_add_u32_e32 v4, 0xc60, v130
	ds_write2_b32 v4, v2, v3 offset1:1
	v_pk_mul_f32 v[2:3], v[16:17], v[124:125] op_sel_hi:[1,0]
	v_add_u32_e32 v4, 0xc68, v130
	ds_write2_b32 v4, v2, v3 offset1:1
	s_waitcnt vmcnt(3)
	v_pk_mul_f32 v[2:3], v[18:19], v[136:137] op_sel_hi:[1,0]
	v_add_u32_e32 v4, 0x1080, v130
	ds_write2_b32 v4, v2, v3 offset1:1
	v_pk_mul_f32 v[2:3], v[20:21], v[136:137] op_sel_hi:[1,0]
	v_add_u32_e32 v4, 0x1088, v130
	ds_write2_b32 v4, v2, v3 offset1:1
	s_waitcnt vmcnt(2)
	v_pk_mul_f32 v[2:3], v[22:23], v[128:129] op_sel_hi:[1,0]
	v_add_u32_e32 v4, 0x14a0, v130
	ds_write2_b32 v4, v2, v3 offset1:1
	v_pk_mul_f32 v[2:3], v[24:25], v[128:129] op_sel_hi:[1,0]
	v_add_u32_e32 v4, 0x14a8, v130
	ds_write2_b32 v4, v2, v3 offset1:1
	s_waitcnt vmcnt(1)
	v_pk_mul_f32 v[2:3], v[26:27], v[138:139] op_sel_hi:[1,0]
	v_add_u32_e32 v4, 0x18c0, v130
	ds_write2_b32 v4, v2, v3 offset1:1
	v_pk_mul_f32 v[2:3], v[28:29], v[138:139] op_sel_hi:[1,0]
	v_add_u32_e32 v4, 0x18c8, v130
	ds_write2_b32 v4, v2, v3 offset1:1
	s_waitcnt vmcnt(0)
	v_pk_mul_f32 v[2:3], v[30:31], v[134:135] op_sel_hi:[1,0]
	v_add_u32_e32 v4, 0x1ce0, v130
	ds_write2_b32 v4, v2, v3 offset1:1
	v_pk_mul_f32 v[2:3], v[32:33], v[134:135] op_sel_hi:[1,0]
	v_add_u32_e32 v4, 0x1ce8, v130
	ds_write2_b32 v4, v2, v3 offset1:1
	s_waitcnt lgkmcnt(0)
	ds_read2_b32 v[6:7], v155 offset0:33 offset1:41
	ds_read2_b32 v[8:9], v155 offset1:8
	ds_read2_b32 v[10:11], v155 offset0:66 offset1:74
	ds_read2_b32 v[12:13], v155 offset0:99 offset1:107
	ds_read2_b32 v[14:15], v155 offset0:132 offset1:140
	ds_read2_b32 v[16:17], v155 offset0:165 offset1:173
	ds_read2_b32 v[18:19], v155 offset0:198 offset1:206
	ds_read2_b32 v[20:21], v155 offset0:231 offset1:239
	v_add_u32_e32 v24, s26, v140
	s_ashr_i32 s77, s76, 31
	v_ashrrev_i32_e32 v25, 31, v24
	v_lshl_add_u64 v[22:23], s[76:77], 1, v[84:85]
	v_lshlrev_b64 v[26:27], 11, v[24:25]
	s_waitcnt lgkmcnt(6)
	v_cvt_pk_bf16_f32 v2, v8, v6
	s_waitcnt lgkmcnt(4)
	v_cvt_pk_bf16_f32 v3, v10, v12
	s_waitcnt lgkmcnt(2)
	v_cvt_pk_bf16_f32 v4, v14, v16
	s_waitcnt lgkmcnt(0)
	v_cvt_pk_bf16_f32 v5, v18, v20
	v_lshl_add_u64 v[26:27], v[22:23], 0, v[26:27]
	v_add_u32_e32 v6, 8, v24
	global_store_dwordx4 v[26:27], v[2:5], off sc1
	s_nop 1
	v_cvt_pk_bf16_f32 v2, v9, v7
	v_ashrrev_i32_e32 v7, 31, v6
	v_cvt_pk_bf16_f32 v3, v11, v13
	v_cvt_pk_bf16_f32 v4, v15, v17
	v_cvt_pk_bf16_f32 v5, v19, v21
	v_lshlrev_b64 v[6:7], 11, v[6:7]
	ds_read2_b32 v[8:9], v155 offset0:49 offset1:57
	ds_read2_b32 v[10:11], v155 offset0:16 offset1:24
	ds_read2_b32 v[12:13], v155 offset0:82 offset1:90
	ds_read2_b32 v[14:15], v155 offset0:115 offset1:123
	ds_read2_b32 v[16:17], v155 offset0:148 offset1:156
	ds_read2_b32 v[18:19], v155 offset0:181 offset1:189
	ds_read2_b32 v[20:21], v155 offset0:214 offset1:222
	ds_read2_b32 v[26:27], v155 offset0:247 offset1:255
	v_lshl_add_u64 v[6:7], v[22:23], 0, v[6:7]
	global_store_dwordx4 v[6:7], v[2:5], off sc1
	v_add_u32_e32 v6, 16, v24
	v_ashrrev_i32_e32 v7, 31, v6
	v_lshlrev_b64 v[6:7], 11, v[6:7]
	s_waitcnt lgkmcnt(6)
	v_cvt_pk_bf16_f32 v2, v10, v8
	s_waitcnt lgkmcnt(4)
	v_cvt_pk_bf16_f32 v3, v12, v14
	s_waitcnt lgkmcnt(2)
	v_cvt_pk_bf16_f32 v4, v16, v18
	s_waitcnt lgkmcnt(0)
	v_cvt_pk_bf16_f32 v5, v20, v26
	v_lshl_add_u64 v[6:7], v[22:23], 0, v[6:7]
	global_store_dwordx4 v[6:7], v[2:5], off sc1
	v_add_u32_e32 v6, 24, v24
	v_ashrrev_i32_e32 v7, 31, v6
	v_lshlrev_b64 v[6:7], 11, v[6:7]
	v_cvt_pk_bf16_f32 v2, v11, v9
	v_cvt_pk_bf16_f32 v3, v13, v15
	v_cvt_pk_bf16_f32 v4, v17, v19
	v_cvt_pk_bf16_f32 v5, v21, v27
	v_lshl_add_u64 v[6:7], v[22:23], 0, v[6:7]
	global_store_dwordx4 v[6:7], v[2:5], off sc1
	s_waitcnt lgkmcnt(0)

; #define LAS __attribute__((address_space(3)))
; __device__ __forceinline__ unsigned pk2(float lo, float hi) { f32x2 v = {lo, hi}; bf2_t b = __builtin_convertvector(v, bf2_t); return __builtin_bit_cast(unsigned, b); }
;     ...
;       for (int i = 0; i < 8; ++i) { const int kk = 8 * i + (lane >> 3); wv[i] = *(const f32x4*)(W + (size_t)(k0 + kk) * N + n0 + 4 * (lane & 7)); gv[i] = gain ? gain[k0 + kk] : 1.0f; }
; #pragma unroll
;       for (int i = 0; i < 8; ++i) { const int kk = 8 * i + (lane >> 3); LAS float* d = scr + kk * 33 + 4 * (lane & 7); d[0] = wv[i][0] * gv[i]; d[1] = wv[i][1] * gv[i]; d[2] = wv[i][2] * gv[i]; d[3] = wv[i][3] * gv[i]; } }
;     asm volatile("s_waitcnt lgkmcnt(0)" ::: "memory");
;     const int c = lane & 7; const int r0 = dst_row(dmode, n0);
; #pragma unroll
;     for (int j = 0; j < 4; ++j) { const int n = (lane >> 3) + 8 * j; const LAS float* s = scr + (8 * c) * 33 + n;
;         u32x4 o; o.x = pk2(s[0 * 33], s[1 * 33]); o.y = pk2(s[2 * 33], s[3 * 33]); o.z = pk2(s[4 * 33], s[5 * 33]); o.w = pk2(s[6 * 33], s[7 * 33]);
;         *(u32x4*)(WT + (size_t)(r0 + n) * pitch + k0 + 8 * c) = o; }
; __device__ __forceinline__ void convert_item(const Args& a, int set, int it, LAS float* scr, int lane) {
;     ...
;     if (r < I_GT) { p0_transpose_item(a.in[I_WGATE], D, 3 * D, a.in[I_MIXN], (bf16_t*)(ws + WS_WG), 0, scr, r, lane); return; } r -= I_GT;
;     if (r < I_SB) { p0_transpose_item(a.in[I_WSB], 512, D, nullptr, (bf16_t*)(ws + WS_WSB), 0, scr, r, lane); return; } r -= I_SB;
;     if (r < I_DS) { p0_transpose_item(a.in[I_WDSA], 256, D, nullptr, (bf16_t*)(ws + WS_WDSA), 0, scr, r, lane, 512); return; } r -= I_DS;
;     if (r < I_DS) { p0_transpose_item(a.in[I_WMEM], 256, D, nullptr, (bf16_t*)(ws + WS_WMEM), 0, scr, r, lane, 512); return; } r -= I_DS;
;     if (r < I_OUT) { p0_transpose_item(a.in[I_WOUT], D, D, nullptr, (bf16_t*)(ws + WS_WOUT), 0, scr, r, lane); return; } r -= I_OUT;
;     if (r < I_UP) { p0_transpose_item(a.in[I_F2W1], D, FF, a.in[I_F2N], (bf16_t*)(ws + WS_W13_2), 1, scr, r, lane); return; } r -= I_UP;
;     if (r < I_UP) { p0_transpose_item(a.in[I_F2W3], D, FF, a.in[I_F2N], (bf16_t*)(ws + WS_W13_2), 2, scr, r, lane); return; } r -= I_UP;
;     p0_transpose_item(a.in[I_F2W2], FF, D, nullptr, (bf16_t*)(ws + WS_W2_2), 0, scr, r, lane);
.LBB0_82:
	s_cmpk_gt_i32 s93, 0x5ff
	s_mov_b64 s[8:9], -1
	s_cbranch_scc0 .LBB0_140
	s_cmpk_gt_u32 s93, 0x6ff
	s_cbranch_scc0 .LBB0_137
	s_cmpk_gt_u32 s93, 0x77f
	s_cbranch_scc0 .LBB0_134
	s_cmpk_gt_u32 s93, 0x7ff
	s_cbranch_scc0 .LBB0_131
	s_cmpk_gt_u32 s93, 0x9ff
	s_cbranch_scc0 .LBB0_128
	s_cmpk_gt_u32 s93, 0xf7f
	s_cbranch_scc0 .LBB0_109
	s_cmpk_gt_u32 s93, 0x14ff
	s_cbranch_scc0 .LBB0_90
	s_add_i32 s8, s79, 0x1d600
	s_and_b32 s8, s8, 0x1ffc0
	s_and_b32 s9, s13, 0x3e0
	s_waitcnt lgkmcnt(3)
	v_or_b32_e32 v4, s8, v140
	s_lshl_b32 s22, s9, 2
	v_lshl_add_u64 v[2:3], v[54:55], 0, s[22:23]
	v_lshlrev_b32_e32 v34, 12, v4
	v_lshl_add_u64 v[30:31], v[2:3], 0, v[34:35]
	s_waitcnt lgkmcnt(2)
	v_add_co_u32_e32 v6, vcc, 0x8000, v30
	v_add_u32_e32 v124, v105, v141
	s_nop 0
	v_addc_co_u32_e32 v7, vcc, 0, v31, vcc
	v_add_co_u32_e32 v10, vcc, 0x10000, v30
	global_load_dwordx4 v[2:5], v[30:31], off
	s_waitcnt lgkmcnt(0)
	global_load_dwordx4 v[6:9], v[6:7], off
	v_addc_co_u32_e32 v11, vcc, 0, v31, vcc
	v_add_co_u32_e32 v14, vcc, 0x18000, v30
	v_add_u32_e32 v126, 0x420, v124
	s_nop 0
	v_addc_co_u32_e32 v15, vcc, 0, v31, vcc
	v_add_co_u32_e32 v18, vcc, s71, v30
	global_load_dwordx4 v[10:13], v[10:11], off
	s_nop 0
	global_load_dwordx4 v[14:17], v[14:15], off
	v_addc_co_u32_e32 v19, vcc, 0, v31, vcc
	v_add_co_u32_e32 v22, vcc, 0x28000, v30
	v_add_u32_e32 v128, 0x428, v124
	s_nop 0
	v_addc_co_u32_e32 v23, vcc, 0, v31, vcc
	global_load_dwordx4 v[18:21], v[18:19], off
	s_nop 0
	global_load_dwordx4 v[22:25], v[22:23], off
	v_add_co_u32_e32 v26, vcc, 0x30000, v30
	v_add_u32_e32 v132, 0x840, v124
	s_nop 0
	v_addc_co_u32_e32 v27, vcc, 0, v31, vcc
	global_load_dwordx4 v[26:29], v[26:27], off
	v_add_co_u32_e32 v30, vcc, 0x38000, v30
	v_add_u32_e32 v134, 0x848, v124
	s_nop 0
	v_addc_co_u32_e32 v31, vcc, 0, v31, vcc
	global_load_dwordx4 v[30:33], v[30:31], off
	v_add_u32_e32 v136, 0xc60, v124
	v_add_u32_e32 v138, 0xc68, v124
	v_add_u32_e32 v156, 0x1080, v124
	v_add_u32_e32 v157, 0x1088, v124
	v_add_u32_e32 v158, 0x14a0, v124
	v_add_u32_e32 v159, 0x14a8, v124
	v_add_u32_e32 v160, 0x18c0, v124
	v_add_u32_e32 v161, 0x18c8, v124
	v_add_u32_e32 v162, 0x1ce0, v124
	v_add_u32_e32 v163, 0x1ce8, v124
	v_or_b32_e32 v34, s9, v140
	s_lshl_b32 s22, s8, 1
	v_mul_u32_u24_e32 v34, 0xb00, v34
	v_lshl_add_u64 v[130:131], v[56:57], 0, s[22:23]
	v_lshlrev_b32_e32 v34, 1, v34
	s_waitcnt vmcnt(7)
	ds_write2_b32 v124, v2, v3 offset1:1
	ds_write2_b32 v124, v4, v5 offset0:2 offset1:3
	s_waitcnt vmcnt(6)
	ds_write2_b32 v126, v6, v7 offset1:1
	ds_write2_b32 v128, v8, v9 offset1:1
	s_waitcnt vmcnt(5)
	ds_write2_b32 v132, v10, v11 offset1:1
	ds_write2_b32 v134, v12, v13 offset1:1
	s_waitcnt vmcnt(4)
	ds_write2_b32 v136, v14, v15 offset1:1
	ds_write2_b32 v138, v16, v17 offset1:1
	s_waitcnt vmcnt(3)
	ds_write2_b32 v156, v18, v19 offset1:1
	ds_write2_b32 v157, v20, v21 offset1:1
	s_waitcnt vmcnt(2)
	ds_write2_b32 v158, v22, v23 offset1:1
	ds_write2_b32 v159, v24, v25 offset1:1
	s_waitcnt vmcnt(1)
	ds_write2_b32 v160, v26, v27 offset1:1
	ds_write2_b32 v161, v28, v29 offset1:1
	s_waitcnt vmcnt(0)
	ds_write2_b32 v162, v30, v31 offset1:1
	ds_write2_b32 v163, v32, v33 offset1:1
	s_waitcnt lgkmcnt(0)
	ds_read2_b32 v[6:7], v155 offset0:33 offset1:41
	ds_read2_b32 v[8:9], v155 offset1:8
	ds_read2_b32 v[10:11], v155 offset0:66 offset1:74
	ds_read2_b32 v[12:13], v155 offset0:99 offset1:107
	ds_read2_b32 v[14:15], v155 offset0:132 offset1:140
	ds_read2_b32 v[16:17], v155 offset0:165 offset1:173
	ds_read2_b32 v[18:19], v155 offset0:198 offset1:206
	ds_read2_b32 v[20:21], v155 offset0:231 offset1:239
	v_lshl_add_u64 v[22:23], v[130:131], 0, v[34:35]
	s_waitcnt lgkmcnt(6)
	v_cvt_pk_bf16_f32 v2, v8, v6
	s_waitcnt lgkmcnt(4)
	v_cvt_pk_bf16_f32 v3, v10, v12
	s_waitcnt lgkmcnt(2)
	v_cvt_pk_bf16_f32 v4, v14, v16
	s_waitcnt lgkmcnt(0)
	v_cvt_pk_bf16_f32 v5, v18, v20
	v_or_b32_e32 v6, s9, v142
	global_store_dwordx4 v[22:23], v[2:5], off sc1
	v_mul_u32_u24_e32 v6, 0xb00, v6
	v_lshlrev_b32_e32 v34, 1, v6
	v_cvt_pk_bf16_f32 v2, v9, v7
	v_cvt_pk_bf16_f32 v3, v11, v13
	v_cvt_pk_bf16_f32 v4, v15, v17
	v_cvt_pk_bf16_f32 v5, v19, v21
	ds_read2_b32 v[8:9], v155 offset0:16 offset1:24
	ds_read2_b32 v[10:11], v155 offset0:49 offset1:57
	ds_read2_b32 v[12:13], v155 offset0:82 offset1:90
	ds_read2_b32 v[14:15], v155 offset0:115 offset1:123
	ds_read2_b32 v[16:17], v155 offset0:148 offset1:156
	ds_read2_b32 v[18:19], v155 offset0:181 offset1:189
	ds_read2_b32 v[20:21], v155 offset0:214 offset1:222
	ds_read2_b32 v[22:23], v155 offset0:247 offset1:255
	v_lshl_add_u64 v[6:7], v[130:131], 0, v[34:35]
	global_store_dwordx4 v[6:7], v[2:5], off sc1
	v_or_b32_e32 v6, s9, v143
	v_mul_u32_u24_e32 v6, 0xb00, v6
	v_lshlrev_b32_e32 v34, 1, v6
	s_waitcnt lgkmcnt(6)
	v_cvt_pk_bf16_f32 v2, v8, v10
	s_waitcnt lgkmcnt(4)
	v_cvt_pk_bf16_f32 v3, v12, v14
	s_waitcnt lgkmcnt(2)
	v_cvt_pk_bf16_f32 v4, v16, v18
	s_waitcnt lgkmcnt(0)
	v_cvt_pk_bf16_f32 v5, v20, v22
	v_lshl_add_u64 v[6:7], v[130:131], 0, v[34:35]
	global_store_dwordx4 v[6:7], v[2:5], off sc1
	v_or_b32_e32 v6, s9, v144
	v_mul_u32_u24_e32 v6, 0xb00, v6
	v_lshlrev_b32_e32 v34, 1, v6
	v_cvt_pk_bf16_f32 v2, v9, v11
	v_cvt_pk_bf16_f32 v3, v13, v15
	v_cvt_pk_bf16_f32 v4, v17, v19
	v_cvt_pk_bf16_f32 v5, v21, v23
	v_lshl_add_u64 v[6:7], v[130:131], 0, v[34:35]
	global_store_dwordx4 v[6:7], v[2:5], off sc1
	s_waitcnt lgkmcnt(0)
	s_mov_b64 s[8:9], 0

; #define LAS __attribute__((address_space(3)))
; __device__ __forceinline__ unsigned pk2(float lo, float hi) { f32x2 v = {lo, hi}; bf2_t b = __builtin_convertvector(v, bf2_t); return __builtin_bit_cast(unsigned, b); }
;     ...
;       for (int i = 0; i < 8; ++i) { const int kk = 8 * i + (lane >> 3); LAS float* d = scr + kk * 33 + 4 * (lane & 7); d[0] = wv[i][0] * gv[i]; d[1] = wv[i][1] * gv[i]; d[2] = wv[i][2] * gv[i]; d[3] = wv[i][3] * gv[i]; } }
;     asm volatile("s_waitcnt lgkmcnt(0)" ::: "memory");
;     const int c = lane & 7; const int r0 = dst_row(dmode, n0);
; #pragma unroll
;     for (int j = 0; j < 4; ++j) { const int n = (lane >> 3) + 8 * j; const LAS float* s = scr + (8 * c) * 33 + n;
;         u32x4 o; o.x = pk2(s[0 * 33], s[1 * 33]); o.y = pk2(s[2 * 33], s[3 * 33]); o.z = pk2(s[4 * 33], s[5 * 33]); o.w = pk2(s[6 * 33], s[7 * 33]);
;         *(u32x4*)(WT + (size_t)(r0 + n) * pitch + k0 + 8 * c) = o; }
.LBB0_107:
	s_waitcnt vmcnt(7)
	v_pk_mul_f32 v[2:3], v[2:3], v[126:127] op_sel_hi:[1,0]
	v_add_u32_e32 v131, v105, v141
	ds_write2_b32 v131, v2, v3 offset1:1
	v_pk_mul_f32 v[2:3], v[4:5], v[126:127] op_sel_hi:[1,0]
	ds_write2_b32 v131, v2, v3 offset0:2 offset1:3
	s_waitcnt vmcnt(6)
	v_pk_mul_f32 v[2:3], v[6:7], v[34:35] op_sel_hi:[1,0]
	v_add_u32_e32 v4, 0x420, v131
	ds_write2_b32 v4, v2, v3 offset1:1
	v_pk_mul_f32 v[2:3], v[8:9], v[34:35] op_sel_hi:[1,0]
	v_add_u32_e32 v4, 0x428, v131
	ds_write2_b32 v4, v2, v3 offset1:1
	s_waitcnt vmcnt(5)
	v_pk_mul_f32 v[2:3], v[10:11], v[130:131] op_sel_hi:[1,0]
	v_add_u32_e32 v4, 0x840, v131
	ds_write2_b32 v4, v2, v3 offset1:1
	v_pk_mul_f32 v[2:3], v[12:13], v[130:131] op_sel_hi:[1,0]
	v_add_u32_e32 v4, 0x848, v131
	ds_write2_b32 v4, v2, v3 offset1:1
	s_waitcnt vmcnt(4)
	v_pk_mul_f32 v[2:3], v[14:15], v[124:125] op_sel_hi:[1,0]
	v_add_u32_e32 v4, 0xc60, v131
	ds_write2_b32 v4, v2, v3 offset1:1
	v_pk_mul_f32 v[2:3], v[16:17], v[124:125] op_sel_hi:[1,0]
	v_add_u32_e32 v4, 0xc68, v131
	ds_write2_b32 v4, v2, v3 offset1:1
	s_waitcnt vmcnt(3)
	v_pk_mul_f32 v[2:3], v[18:19], v[134:135] op_sel_hi:[1,0]
	v_add_u32_e32 v4, 0x1080, v131
	ds_write2_b32 v4, v2, v3 offset1:1
	v_pk_mul_f32 v[2:3], v[20:21], v[134:135] op_sel_hi:[1,0]
	v_add_u32_e32 v4, 0x1088, v131
	ds_write2_b32 v4, v2, v3 offset1:1
	s_waitcnt vmcnt(2)
	v_pk_mul_f32 v[2:3], v[22:23], v[128:129] op_sel_hi:[1,0]
	v_add_u32_e32 v4, 0x14a0, v131
	ds_write2_b32 v4, v2, v3 offset1:1
	v_pk_mul_f32 v[2:3], v[24:25], v[128:129] op_sel_hi:[1,0]
	v_add_u32_e32 v4, 0x14a8, v131
	ds_write2_b32 v4, v2, v3 offset1:1
	s_waitcnt vmcnt(1)
	v_pk_mul_f32 v[2:3], v[26:27], v[136:137] op_sel_hi:[1,0]
	v_add_u32_e32 v4, 0x18c0, v131
	ds_write2_b32 v4, v2, v3 offset1:1
	v_pk_mul_f32 v[2:3], v[28:29], v[136:137] op_sel_hi:[1,0]
	v_add_u32_e32 v4, 0x18c8, v131
	ds_write2_b32 v4, v2, v3 offset1:1
	s_waitcnt vmcnt(0)
	v_pk_mul_f32 v[2:3], v[30:31], v[132:133] op_sel_hi:[1,0]
	v_add_u32_e32 v4, 0x1ce0, v131
	ds_write2_b32 v4, v2, v3 offset1:1
	v_pk_mul_f32 v[2:3], v[32:33], v[132:133] op_sel_hi:[1,0]
	v_add_u32_e32 v4, 0x1ce8, v131
	ds_write2_b32 v4, v2, v3 offset1:1
	s_waitcnt lgkmcnt(0)
	s_lshl_b32 s9, s27, 6
	s_and_b32 s9, s9, 0x1f00
	s_and_b32 s8, s8, 0x60
	ds_read2_b32 v[6:7], v155 offset0:33 offset1:41
	ds_read2_b32 v[8:9], v155 offset1:8
	ds_read2_b32 v[10:11], v155 offset0:66 offset1:74
	ds_read2_b32 v[12:13], v155 offset0:99 offset1:107
	ds_read2_b32 v[14:15], v155 offset0:132 offset1:140
	ds_read2_b32 v[16:17], v155 offset0:165 offset1:173
	ds_read2_b32 v[18:19], v155 offset0:198 offset1:206
	ds_read2_b32 v[20:21], v155 offset0:231 offset1:239
	s_or_b32 s8, s8, s9
	s_bitset1_b32 s8, 7
	s_and_b32 s9, 0xffff, s26
	s_lshl_b32 s22, s9, 1
	s_waitcnt lgkmcnt(6)
	v_cvt_pk_bf16_f32 v2, v8, v6
	v_or_b32_e32 v6, s8, v140
	v_lshl_add_u64 v[22:23], v[60:61], 0, s[22:23]
	v_lshlrev_b32_e32 v34, 11, v6
	s_waitcnt lgkmcnt(4)
	v_cvt_pk_bf16_f32 v3, v10, v12
	s_waitcnt lgkmcnt(2)
	v_cvt_pk_bf16_f32 v4, v14, v16
	s_waitcnt lgkmcnt(0)
	v_cvt_pk_bf16_f32 v5, v18, v20
	v_lshl_add_u64 v[24:25], v[22:23], 0, v[34:35]
	global_store_dwordx4 v[24:25], v[2:5], off sc1
	v_or_b32_e32 v6, s8, v142
	v_lshlrev_b32_e32 v34, 11, v6
	v_cvt_pk_bf16_f32 v2, v9, v7
	v_cvt_pk_bf16_f32 v3, v11, v13
	v_cvt_pk_bf16_f32 v4, v15, v17
	v_cvt_pk_bf16_f32 v5, v19, v21
	ds_read2_b32 v[8:9], v155 offset0:49 offset1:57
	ds_read2_b32 v[10:11], v155 offset0:16 offset1:24
	ds_read2_b32 v[12:13], v155 offset0:82 offset1:90
	ds_read2_b32 v[14:15], v155 offset0:115 offset1:123
	ds_read2_b32 v[16:17], v155 offset0:148 offset1:156
	ds_read2_b32 v[18:19], v155 offset0:181 offset1:189
	ds_read2_b32 v[20:21], v155 offset0:214 offset1:222
	ds_read2_b32 v[24:25], v155 offset0:247 offset1:255
	v_lshl_add_u64 v[6:7], v[22:23], 0, v[34:35]
	global_store_dwordx4 v[6:7], v[2:5], off sc1
	v_or_b32_e32 v6, s8, v143
	v_lshlrev_b32_e32 v34, 11, v6
	s_waitcnt lgkmcnt(6)
	v_cvt_pk_bf16_f32 v2, v10, v8
	s_waitcnt lgkmcnt(4)
	v_cvt_pk_bf16_f32 v3, v12, v14
	s_waitcnt lgkmcnt(2)
	v_cvt_pk_bf16_f32 v4, v16, v18
	s_waitcnt lgkmcnt(0)
	v_cvt_pk_bf16_f32 v5, v20, v24
	v_lshl_add_u64 v[6:7], v[22:23], 0, v[34:35]
	global_store_dwordx4 v[6:7], v[2:5], off sc1
	v_or_b32_e32 v6, s8, v144
	v_lshlrev_b32_e32 v34, 11, v6
	v_cvt_pk_bf16_f32 v2, v11, v9
	v_cvt_pk_bf16_f32 v3, v13, v15
	v_cvt_pk_bf16_f32 v4, v17, v19
	v_cvt_pk_bf16_f32 v5, v21, v25
	v_lshl_add_u64 v[6:7], v[22:23], 0, v[34:35]
	global_store_dwordx4 v[6:7], v[2:5], off sc1
	s_waitcnt lgkmcnt(0)

; #define LAS __attribute__((address_space(3)))
; __device__ __forceinline__ unsigned pk2(float lo, float hi) { f32x2 v = {lo, hi}; bf2_t b = __builtin_convertvector(v, bf2_t); return __builtin_bit_cast(unsigned, b); }
;     ...
;       for (int i = 0; i < 8; ++i) { const int kk = 8 * i + (lane >> 3); LAS float* d = scr + kk * 33 + 4 * (lane & 7); d[0] = wv[i][0] * gv[i]; d[1] = wv[i][1] * gv[i]; d[2] = wv[i][2] * gv[i]; d[3] = wv[i][3] * gv[i]; } }
;     asm volatile("s_waitcnt lgkmcnt(0)" ::: "memory");
;     const int c = lane & 7; const int r0 = dst_row(dmode, n0);
; #pragma unroll
;     for (int j = 0; j < 4; ++j) { const int n = (lane >> 3) + 8 * j; const LAS float* s = scr + (8 * c) * 33 + n;
;         u32x4 o; o.x = pk2(s[0 * 33], s[1 * 33]); o.y = pk2(s[2 * 33], s[3 * 33]); o.z = pk2(s[4 * 33], s[5 * 33]); o.w = pk2(s[6 * 33], s[7 * 33]);
;         *(u32x4*)(WT + (size_t)(r0 + n) * pitch + k0 + 8 * c) = o; }
.LBB0_126:
	s_waitcnt vmcnt(7)
	v_pk_mul_f32 v[2:3], v[2:3], v[126:127] op_sel_hi:[1,0]
	v_add_u32_e32 v131, v105, v141
	ds_write2_b32 v131, v2, v3 offset1:1
	v_pk_mul_f32 v[2:3], v[4:5], v[126:127] op_sel_hi:[1,0]
	ds_write2_b32 v131, v2, v3 offset0:2 offset1:3
	s_waitcnt vmcnt(6)
	v_pk_mul_f32 v[2:3], v[6:7], v[34:35] op_sel_hi:[1,0]
	v_add_u32_e32 v4, 0x420, v131
	ds_write2_b32 v4, v2, v3 offset1:1
	v_pk_mul_f32 v[2:3], v[8:9], v[34:35] op_sel_hi:[1,0]
	v_add_u32_e32 v4, 0x428, v131
	ds_write2_b32 v4, v2, v3 offset1:1
	s_waitcnt vmcnt(5)
	v_pk_mul_f32 v[2:3], v[10:11], v[130:131] op_sel_hi:[1,0]
	v_add_u32_e32 v4, 0x840, v131
	ds_write2_b32 v4, v2, v3 offset1:1
	v_pk_mul_f32 v[2:3], v[12:13], v[130:131] op_sel_hi:[1,0]
	v_add_u32_e32 v4, 0x848, v131
	ds_write2_b32 v4, v2, v3 offset1:1
	s_waitcnt vmcnt(4)
	v_pk_mul_f32 v[2:3], v[14:15], v[124:125] op_sel_hi:[1,0]
	v_add_u32_e32 v4, 0xc60, v131
	ds_write2_b32 v4, v2, v3 offset1:1
	v_pk_mul_f32 v[2:3], v[16:17], v[124:125] op_sel_hi:[1,0]
	v_add_u32_e32 v4, 0xc68, v131
	ds_write2_b32 v4, v2, v3 offset1:1
	s_waitcnt vmcnt(3)
	v_pk_mul_f32 v[2:3], v[18:19], v[134:135] op_sel_hi:[1,0]
	v_add_u32_e32 v4, 0x1080, v131
	ds_write2_b32 v4, v2, v3 offset1:1
	v_pk_mul_f32 v[2:3], v[20:21], v[134:135] op_sel_hi:[1,0]
	v_add_u32_e32 v4, 0x1088, v131
	ds_write2_b32 v4, v2, v3 offset1:1
	s_waitcnt vmcnt(2)
	v_pk_mul_f32 v[2:3], v[22:23], v[128:129] op_sel_hi:[1,0]
	v_add_u32_e32 v4, 0x14a0, v131
	ds_write2_b32 v4, v2, v3 offset1:1
	v_pk_mul_f32 v[2:3], v[24:25], v[128:129] op_sel_hi:[1,0]
	v_add_u32_e32 v4, 0x14a8, v131
	ds_write2_b32 v4, v2, v3 offset1:1
	s_waitcnt vmcnt(1)
	v_pk_mul_f32 v[2:3], v[26:27], v[136:137] op_sel_hi:[1,0]
	v_add_u32_e32 v4, 0x18c0, v131
	ds_write2_b32 v4, v2, v3 offset1:1
	v_pk_mul_f32 v[2:3], v[28:29], v[136:137] op_sel_hi:[1,0]
	v_add_u32_e32 v4, 0x18c8, v131
	ds_write2_b32 v4, v2, v3 offset1:1
	s_waitcnt vmcnt(0)
	v_pk_mul_f32 v[2:3], v[30:31], v[132:133] op_sel_hi:[1,0]
	v_add_u32_e32 v4, 0x1ce0, v131
	ds_write2_b32 v4, v2, v3 offset1:1
	v_pk_mul_f32 v[2:3], v[32:33], v[132:133] op_sel_hi:[1,0]
	v_add_u32_e32 v4, 0x1ce8, v131
	ds_write2_b32 v4, v2, v3 offset1:1
	s_waitcnt lgkmcnt(0)
	s_lshl_b32 s8, s27, 5
	s_lshl_b32 s9, s27, 6
	ds_read2_b32 v[6:7], v155 offset0:33 offset1:41
	ds_read2_b32 v[8:9], v155 offset1:8
	ds_read2_b32 v[10:11], v155 offset0:66 offset1:74
	ds_read2_b32 v[12:13], v155 offset0:99 offset1:107
	ds_read2_b32 v[14:15], v155 offset0:132 offset1:140
	ds_read2_b32 v[16:17], v155 offset0:165 offset1:173
	ds_read2_b32 v[18:19], v155 offset0:198 offset1:206
	ds_read2_b32 v[20:21], v155 offset0:231 offset1:239
	s_and_b32 s9, s9, 0x1f00
	s_and_b32 s8, s8, 0x60
	s_or_b32 s8, s9, s8
	s_and_b32 s9, 0xffff, s26
	s_lshl_b32 s22, s9, 1
	s_waitcnt lgkmcnt(6)
	v_cvt_pk_bf16_f32 v2, v8, v6
	v_or_b32_e32 v6, s8, v140
	v_lshl_add_u64 v[22:23], v[60:61], 0, s[22:23]
	v_lshlrev_b32_e32 v34, 11, v6
	s_waitcnt lgkmcnt(4)
	v_cvt_pk_bf16_f32 v3, v10, v12
	s_waitcnt lgkmcnt(2)
	v_cvt_pk_bf16_f32 v4, v14, v16
	s_waitcnt lgkmcnt(0)
	v_cvt_pk_bf16_f32 v5, v18, v20
	v_lshl_add_u64 v[24:25], v[22:23], 0, v[34:35]
	global_store_dwordx4 v[24:25], v[2:5], off sc1
	v_or_b32_e32 v6, s8, v142
	v_lshlrev_b32_e32 v34, 11, v6
	v_cvt_pk_bf16_f32 v2, v9, v7
	v_cvt_pk_bf16_f32 v3, v11, v13
	v_cvt_pk_bf16_f32 v4, v15, v17
	v_cvt_pk_bf16_f32 v5, v19, v21
	ds_read2_b32 v[8:9], v155 offset0:49 offset1:57
	ds_read2_b32 v[10:11], v155 offset0:16 offset1:24
	ds_read2_b32 v[12:13], v155 offset0:82 offset1:90
	ds_read2_b32 v[14:15], v155 offset0:115 offset1:123
	ds_read2_b32 v[16:17], v155 offset0:148 offset1:156
	ds_read2_b32 v[18:19], v155 offset0:181 offset1:189
	ds_read2_b32 v[20:21], v155 offset0:214 offset1:222
	ds_read2_b32 v[24:25], v155 offset0:247 offset1:255
	v_lshl_add_u64 v[6:7], v[22:23], 0, v[34:35]
	global_store_dwordx4 v[6:7], v[2:5], off sc1
	v_or_b32_e32 v6, s8, v143
	v_lshlrev_b32_e32 v34, 11, v6
	s_waitcnt lgkmcnt(6)
	v_cvt_pk_bf16_f32 v2, v10, v8
	s_waitcnt lgkmcnt(4)
	v_cvt_pk_bf16_f32 v3, v12, v14
	s_waitcnt lgkmcnt(2)
	v_cvt_pk_bf16_f32 v4, v16, v18
	s_waitcnt lgkmcnt(0)
	v_cvt_pk_bf16_f32 v5, v20, v24
	v_lshl_add_u64 v[6:7], v[22:23], 0, v[34:35]
	global_store_dwordx4 v[6:7], v[2:5], off sc1
	v_or_b32_e32 v6, s8, v144
	v_lshlrev_b32_e32 v34, 11, v6
	v_cvt_pk_bf16_f32 v2, v11, v9
	v_cvt_pk_bf16_f32 v3, v13, v15
	v_cvt_pk_bf16_f32 v4, v17, v19
	v_cvt_pk_bf16_f32 v5, v21, v25
	v_lshl_add_u64 v[6:7], v[22:23], 0, v[34:35]
	global_store_dwordx4 v[6:7], v[2:5], off sc1
	s_waitcnt lgkmcnt(0)

; #define LAS __attribute__((address_space(3)))
; __device__ __forceinline__ unsigned pk2(float lo, float hi) { f32x2 v = {lo, hi}; bf2_t b = __builtin_convertvector(v, bf2_t); return __builtin_bit_cast(unsigned, b); }
;     ...
;       for (int i = 0; i < 8; ++i) { const int kk = 8 * i + (lane >> 3); wv[i] = *(const f32x4*)(W + (size_t)(k0 + kk) * N + n0 + 4 * (lane & 7)); gv[i] = gain ? gain[k0 + kk] : 1.0f; }
; #pragma unroll
;       for (int i = 0; i < 8; ++i) { const int kk = 8 * i + (lane >> 3); LAS float* d = scr + kk * 33 + 4 * (lane & 7); d[0] = wv[i][0] * gv[i]; d[1] = wv[i][1] * gv[i]; d[2] = wv[i][2] * gv[i]; d[3] = wv[i][3] * gv[i]; } }
;     asm volatile("s_waitcnt lgkmcnt(0)" ::: "memory");
;     const int c = lane & 7; const int r0 = dst_row(dmode, n0);
; #pragma unroll
;     for (int j = 0; j < 4; ++j) { const int n = (lane >> 3) + 8 * j; const LAS float* s = scr + (8 * c) * 33 + n;
;         u32x4 o; o.x = pk2(s[0 * 33], s[1 * 33]); o.y = pk2(s[2 * 33], s[3 * 33]); o.z = pk2(s[4 * 33], s[5 * 33]); o.w = pk2(s[6 * 33], s[7 * 33]);
;         *(u32x4*)(WT + (size_t)(r0 + n) * pitch + k0 + 8 * c) = o; }
.LBB0_128:
	s_andn2_b64 vcc, exec, s[8:9]
	s_cbranch_vccnz .LBB0_130
	s_add_i32 s8, s79, 0x1f000
	s_and_b32 s8, s8, 0x1ffc0
	s_and_b32 s9, s13, 0x3e0
	s_waitcnt lgkmcnt(3)
	v_or_b32_e32 v4, s8, v140
	s_lshl_b32 s22, s9, 2
	v_lshl_add_u64 v[2:3], v[64:65], 0, s[22:23]
	v_lshlrev_b32_e32 v34, 12, v4
	v_lshl_add_u64 v[30:31], v[2:3], 0, v[34:35]
	s_waitcnt lgkmcnt(2)
	v_add_co_u32_e32 v6, vcc, 0x8000, v30
	v_add_u32_e32 v124, v105, v141
	s_nop 0
	v_addc_co_u32_e32 v7, vcc, 0, v31, vcc
	v_add_co_u32_e32 v10, vcc, 0x10000, v30
	global_load_dwordx4 v[2:5], v[30:31], off
	s_waitcnt lgkmcnt(0)
	global_load_dwordx4 v[6:9], v[6:7], off
	v_addc_co_u32_e32 v11, vcc, 0, v31, vcc
	v_add_co_u32_e32 v14, vcc, 0x18000, v30
	v_add_u32_e32 v126, 0x420, v124
	s_nop 0
	v_addc_co_u32_e32 v15, vcc, 0, v31, vcc
	v_add_co_u32_e32 v18, vcc, s71, v30
	global_load_dwordx4 v[10:13], v[10:11], off
	s_nop 0
	global_load_dwordx4 v[14:17], v[14:15], off
	v_addc_co_u32_e32 v19, vcc, 0, v31, vcc
	v_add_co_u32_e32 v22, vcc, 0x28000, v30
	v_add_u32_e32 v128, 0x428, v124
	s_nop 0
	v_addc_co_u32_e32 v23, vcc, 0, v31, vcc
	global_load_dwordx4 v[18:21], v[18:19], off
	s_nop 0
	global_load_dwordx4 v[22:25], v[22:23], off
	v_add_co_u32_e32 v26, vcc, 0x30000, v30
	v_add_u32_e32 v132, 0x840, v124
	s_nop 0
	v_addc_co_u32_e32 v27, vcc, 0, v31, vcc
	global_load_dwordx4 v[26:29], v[26:27], off
	v_add_co_u32_e32 v30, vcc, 0x38000, v30
	v_add_u32_e32 v134, 0x848, v124
	s_nop 0
	v_addc_co_u32_e32 v31, vcc, 0, v31, vcc
	global_load_dwordx4 v[30:33], v[30:31], off
	v_add_u32_e32 v136, 0xc60, v124
	v_add_u32_e32 v138, 0xc68, v124
	v_add_u32_e32 v156, 0x1080, v124
	v_add_u32_e32 v157, 0x1088, v124
	v_add_u32_e32 v158, 0x14a0, v124
	v_add_u32_e32 v159, 0x14a8, v124
	v_add_u32_e32 v160, 0x18c0, v124
	v_add_u32_e32 v161, 0x18c8, v124
	v_add_u32_e32 v162, 0x1ce0, v124
	v_add_u32_e32 v163, 0x1ce8, v124
	v_or_b32_e32 v34, s9, v140
	s_lshl_b32 s22, s8, 1
	v_lshl_add_u64 v[130:131], v[66:67], 0, s[22:23]
	v_lshlrev_b32_e32 v34, 11, v34
	s_waitcnt vmcnt(7)
	ds_write2_b32 v124, v2, v3 offset1:1
	ds_write2_b32 v124, v4, v5 offset0:2 offset1:3
	s_waitcnt vmcnt(6)
	ds_write2_b32 v126, v6, v7 offset1:1
	ds_write2_b32 v128, v8, v9 offset1:1
	s_waitcnt vmcnt(5)
	ds_write2_b32 v132, v10, v11 offset1:1
	ds_write2_b32 v134, v12, v13 offset1:1
	s_waitcnt vmcnt(4)
	ds_write2_b32 v136, v14, v15 offset1:1
	ds_write2_b32 v138, v16, v17 offset1:1
	s_waitcnt vmcnt(3)
	ds_write2_b32 v156, v18, v19 offset1:1
	ds_write2_b32 v157, v20, v21 offset1:1
	s_waitcnt vmcnt(2)
	ds_write2_b32 v158, v22, v23 offset1:1
	ds_write2_b32 v159, v24, v25 offset1:1
	s_waitcnt vmcnt(1)
	ds_write2_b32 v160, v26, v27 offset1:1
	ds_write2_b32 v161, v28, v29 offset1:1
	s_waitcnt vmcnt(0)
	ds_write2_b32 v162, v30, v31 offset1:1
	ds_write2_b32 v163, v32, v33 offset1:1
	s_waitcnt lgkmcnt(0)
	ds_read2_b32 v[6:7], v155 offset0:33 offset1:41
	ds_read2_b32 v[8:9], v155 offset1:8
	ds_read2_b32 v[10:11], v155 offset0:66 offset1:74
	ds_read2_b32 v[12:13], v155 offset0:99 offset1:107
	ds_read2_b32 v[14:15], v155 offset0:132 offset1:140
	ds_read2_b32 v[16:17], v155 offset0:165 offset1:173
	ds_read2_b32 v[18:19], v155 offset0:198 offset1:206
	ds_read2_b32 v[20:21], v155 offset0:231 offset1:239
	v_lshl_add_u64 v[22:23], v[130:131], 0, v[34:35]
	s_waitcnt lgkmcnt(6)
	v_cvt_pk_bf16_f32 v2, v8, v6
	s_waitcnt lgkmcnt(4)
	v_cvt_pk_bf16_f32 v3, v10, v12
	s_waitcnt lgkmcnt(2)
	v_cvt_pk_bf16_f32 v4, v14, v16
	s_waitcnt lgkmcnt(0)
	v_cvt_pk_bf16_f32 v5, v18, v20
	global_store_dwordx4 v[22:23], v[2:5], off sc1
	v_cvt_pk_bf16_f32 v6, v9, v7
	v_cvt_pk_bf16_f32 v7, v11, v13
	v_cvt_pk_bf16_f32 v8, v15, v17
	v_cvt_pk_bf16_f32 v9, v19, v21
	v_or_b32_e32 v2, s9, v142
	ds_read2_b32 v[10:11], v155 offset0:49 offset1:57
	ds_read2_b32 v[12:13], v155 offset0:16 offset1:24
	ds_read2_b32 v[14:15], v155 offset0:82 offset1:90
	ds_read2_b32 v[16:17], v155 offset0:115 offset1:123
	ds_read2_b32 v[18:19], v155 offset0:148 offset1:156
	ds_read2_b32 v[20:21], v155 offset0:181 offset1:189
	ds_read2_b32 v[22:23], v155 offset0:214 offset1:222
	ds_read2_b32 v[24:25], v155 offset0:247 offset1:255
	v_lshlrev_b32_e32 v34, 11, v2
	v_lshl_add_u64 v[2:3], v[130:131], 0, v[34:35]
	global_store_dwordx4 v[2:3], v[6:9], off sc1
	s_waitcnt lgkmcnt(6)
	v_cvt_pk_bf16_f32 v2, v12, v10
	s_waitcnt lgkmcnt(4)
	v_cvt_pk_bf16_f32 v3, v14, v16
	v_or_b32_e32 v6, s9, v143
	v_lshlrev_b32_e32 v34, 11, v6
	s_waitcnt lgkmcnt(2)
	v_cvt_pk_bf16_f32 v4, v18, v20
	s_waitcnt lgkmcnt(0)
	v_cvt_pk_bf16_f32 v5, v22, v24
	v_lshl_add_u64 v[6:7], v[130:131], 0, v[34:35]
	global_store_dwordx4 v[6:7], v[2:5], off sc1
	v_or_b32_e32 v6, s9, v144
	v_lshlrev_b32_e32 v34, 11, v6
	v_cvt_pk_bf16_f32 v2, v13, v11
	v_cvt_pk_bf16_f32 v3, v15, v17
	v_cvt_pk_bf16_f32 v4, v19, v21
	v_cvt_pk_bf16_f32 v5, v23, v25
	v_lshl_add_u64 v[6:7], v[130:131], 0, v[34:35]
	global_store_dwordx4 v[6:7], v[2:5], off sc1
	s_waitcnt lgkmcnt(0)

; #define LAS __attribute__((address_space(3)))
; __device__ __forceinline__ unsigned pk2(float lo, float hi) { f32x2 v = {lo, hi}; bf2_t b = __builtin_convertvector(v, bf2_t); return __builtin_bit_cast(unsigned, b); }
;     ...
;       for (int i = 0; i < 8; ++i) { const int kk = 8 * i + (lane >> 3); wv[i] = *(const f32x4*)(W + (size_t)(k0 + kk) * N + n0 + 4 * (lane & 7)); gv[i] = gain ? gain[k0 + kk] : 1.0f; }
; #pragma unroll
;       for (int i = 0; i < 8; ++i) { const int kk = 8 * i + (lane >> 3); LAS float* d = scr + kk * 33 + 4 * (lane & 7); d[0] = wv[i][0] * gv[i]; d[1] = wv[i][1] * gv[i]; d[2] = wv[i][2] * gv[i]; d[3] = wv[i][3] * gv[i]; } }
;     asm volatile("s_waitcnt lgkmcnt(0)" ::: "memory");
;     const int c = lane & 7; const int r0 = dst_row(dmode, n0);
; #pragma unroll
;     for (int j = 0; j < 4; ++j) { const int n = (lane >> 3) + 8 * j; const LAS float* s = scr + (8 * c) * 33 + n;
;         u32x4 o; o.x = pk2(s[0 * 33], s[1 * 33]); o.y = pk2(s[2 * 33], s[3 * 33]); o.z = pk2(s[4 * 33], s[5 * 33]); o.w = pk2(s[6 * 33], s[7 * 33]);
;         *(u32x4*)(WT + (size_t)(r0 + n) * pitch + k0 + 8 * c) = o; }
.LBB0_131:
	s_andn2_b64 vcc, exec, s[8:9]
	s_cbranch_vccnz .LBB0_133
	s_and_b32 s8, s79, 0x1c0
	s_and_b32 s9, s13, 0x3e0
	s_waitcnt lgkmcnt(3)
	v_bitop3_b32 v4, s8, v140, v154 bitop3:0xde
	s_lshl_b32 s22, s9, 2
	v_lshl_add_u64 v[2:3], v[86:87], 0, s[22:23]
	v_lshlrev_b32_e32 v34, 12, v4
	v_lshl_add_u64 v[30:31], v[2:3], 0, v[34:35]
	s_waitcnt lgkmcnt(2)
	v_add_co_u32_e32 v6, vcc, 0x8000, v30
	v_add_u32_e32 v124, v105, v141
	s_nop 0
	v_addc_co_u32_e32 v7, vcc, 0, v31, vcc
	v_add_co_u32_e32 v10, vcc, 0x10000, v30
	global_load_dwordx4 v[2:5], v[30:31], off
	s_waitcnt lgkmcnt(0)
	global_load_dwordx4 v[6:9], v[6:7], off
	v_addc_co_u32_e32 v11, vcc, 0, v31, vcc
	v_add_co_u32_e32 v14, vcc, 0x18000, v30
	v_add_u32_e32 v126, 0x420, v124
	s_nop 0
	v_addc_co_u32_e32 v15, vcc, 0, v31, vcc
	v_add_co_u32_e32 v18, vcc, s71, v30
	global_load_dwordx4 v[10:13], v[10:11], off
	s_nop 0
	global_load_dwordx4 v[14:17], v[14:15], off
	v_addc_co_u32_e32 v19, vcc, 0, v31, vcc
	v_add_co_u32_e32 v22, vcc, 0x28000, v30
	v_add_u32_e32 v128, 0x428, v124
	s_nop 0
	v_addc_co_u32_e32 v23, vcc, 0, v31, vcc
	global_load_dwordx4 v[18:21], v[18:19], off
	s_nop 0
	global_load_dwordx4 v[22:25], v[22:23], off
	v_add_co_u32_e32 v26, vcc, 0x30000, v30
	v_add_u32_e32 v132, 0x840, v124
	s_nop 0
	v_addc_co_u32_e32 v27, vcc, 0, v31, vcc
	global_load_dwordx4 v[26:29], v[26:27], off
	v_add_co_u32_e32 v30, vcc, 0x38000, v30
	v_add_u32_e32 v134, 0x848, v124
	s_nop 0
	v_addc_co_u32_e32 v31, vcc, 0, v31, vcc
	global_load_dwordx4 v[30:33], v[30:31], off
	v_add_u32_e32 v136, 0xc60, v124
	v_add_u32_e32 v138, 0xc68, v124
	v_add_u32_e32 v156, 0x1080, v124
	v_add_u32_e32 v157, 0x1088, v124
	v_add_u32_e32 v158, 0x14a0, v124
	v_add_u32_e32 v159, 0x14a8, v124
	v_add_u32_e32 v160, 0x18c0, v124
	v_add_u32_e32 v161, 0x18c8, v124
	v_add_u32_e32 v162, 0x1ce0, v124
	v_add_u32_e32 v163, 0x1ce8, v124
	s_xor_b32 s8, s8, 0x100
	v_or_b32_e32 v34, s9, v140
	s_lshl_b32 s22, s8, 1
	v_lshl_add_u64 v[130:131], v[68:69], 0, s[22:23]
	v_lshlrev_b32_e32 v34, 10, v34
	s_waitcnt vmcnt(7)
	ds_write2_b32 v124, v2, v3 offset1:1
	ds_write2_b32 v124, v4, v5 offset0:2 offset1:3
	s_waitcnt vmcnt(6)
	ds_write2_b32 v126, v6, v7 offset1:1
	ds_write2_b32 v128, v8, v9 offset1:1
	s_waitcnt vmcnt(5)
	ds_write2_b32 v132, v10, v11 offset1:1
	ds_write2_b32 v134, v12, v13 offset1:1
	s_waitcnt vmcnt(4)
	ds_write2_b32 v136, v14, v15 offset1:1
	ds_write2_b32 v138, v16, v17 offset1:1
	s_waitcnt vmcnt(3)
	ds_write2_b32 v156, v18, v19 offset1:1
	ds_write2_b32 v157, v20, v21 offset1:1
	s_waitcnt vmcnt(2)
	ds_write2_b32 v158, v22, v23 offset1:1
	ds_write2_b32 v159, v24, v25 offset1:1
	s_waitcnt vmcnt(1)
	ds_write2_b32 v160, v26, v27 offset1:1
	ds_write2_b32 v161, v28, v29 offset1:1
	s_waitcnt vmcnt(0)
	ds_write2_b32 v162, v30, v31 offset1:1
	ds_write2_b32 v163, v32, v33 offset1:1
	s_waitcnt lgkmcnt(0)
	ds_read2_b32 v[6:7], v155 offset0:33 offset1:41
	ds_read2_b32 v[8:9], v155 offset1:8
	ds_read2_b32 v[10:11], v155 offset0:66 offset1:74
	ds_read2_b32 v[12:13], v155 offset0:99 offset1:107
	ds_read2_b32 v[14:15], v155 offset0:132 offset1:140
	ds_read2_b32 v[16:17], v155 offset0:165 offset1:173
	ds_read2_b32 v[18:19], v155 offset0:198 offset1:206
	ds_read2_b32 v[20:21], v155 offset0:231 offset1:239
	v_lshl_add_u64 v[22:23], v[130:131], 0, v[34:35]
	s_waitcnt lgkmcnt(6)
	v_cvt_pk_bf16_f32 v2, v8, v6
	s_waitcnt lgkmcnt(4)
	v_cvt_pk_bf16_f32 v3, v10, v12
	s_waitcnt lgkmcnt(2)
	v_cvt_pk_bf16_f32 v4, v14, v16
	s_waitcnt lgkmcnt(0)
	v_cvt_pk_bf16_f32 v5, v18, v20
	global_store_dwordx4 v[22:23], v[2:5], off sc1
	v_or_b32_e32 v6, s9, v142
	v_lshlrev_b32_e32 v34, 10, v6
	v_cvt_pk_bf16_f32 v2, v9, v7
	v_cvt_pk_bf16_f32 v3, v11, v13
	v_cvt_pk_bf16_f32 v4, v15, v17
	v_cvt_pk_bf16_f32 v5, v19, v21
	ds_read2_b32 v[8:9], v155 offset0:49 offset1:57
	ds_read2_b32 v[10:11], v155 offset0:16 offset1:24
	ds_read2_b32 v[12:13], v155 offset0:82 offset1:90
	ds_read2_b32 v[14:15], v155 offset0:115 offset1:123
	ds_read2_b32 v[16:17], v155 offset0:148 offset1:156
	ds_read2_b32 v[18:19], v155 offset0:181 offset1:189
	ds_read2_b32 v[20:21], v155 offset0:214 offset1:222
	ds_read2_b32 v[22:23], v155 offset0:247 offset1:255
	v_lshl_add_u64 v[6:7], v[130:131], 0, v[34:35]
	global_store_dwordx4 v[6:7], v[2:5], off sc1
	v_or_b32_e32 v6, s9, v143
	v_lshlrev_b32_e32 v34, 10, v6
	s_waitcnt lgkmcnt(6)
	v_cvt_pk_bf16_f32 v2, v10, v8
	s_waitcnt lgkmcnt(4)
	v_cvt_pk_bf16_f32 v3, v12, v14
	s_waitcnt lgkmcnt(2)
	v_cvt_pk_bf16_f32 v4, v16, v18
	s_waitcnt lgkmcnt(0)
	v_cvt_pk_bf16_f32 v5, v20, v22
	v_lshl_add_u64 v[6:7], v[130:131], 0, v[34:35]
	global_store_dwordx4 v[6:7], v[2:5], off sc1
	v_or_b32_e32 v6, s9, v144
	v_lshlrev_b32_e32 v34, 10, v6
	v_cvt_pk_bf16_f32 v2, v11, v9
	v_cvt_pk_bf16_f32 v3, v13, v15
	v_cvt_pk_bf16_f32 v4, v17, v19
	v_cvt_pk_bf16_f32 v5, v21, v23
	v_lshl_add_u64 v[6:7], v[130:131], 0, v[34:35]
	global_store_dwordx4 v[6:7], v[2:5], off sc1
	s_waitcnt lgkmcnt(0)

; #define LAS __attribute__((address_space(3)))
; __device__ __forceinline__ unsigned pk2(float lo, float hi) { f32x2 v = {lo, hi}; bf2_t b = __builtin_convertvector(v, bf2_t); return __builtin_bit_cast(unsigned, b); }
;     ...
;       for (int i = 0; i < 8; ++i) { const int kk = 8 * i + (lane >> 3); wv[i] = *(const f32x4*)(W + (size_t)(k0 + kk) * N + n0 + 4 * (lane & 7)); gv[i] = gain ? gain[k0 + kk] : 1.0f; }
; #pragma unroll
;       for (int i = 0; i < 8; ++i) { const int kk = 8 * i + (lane >> 3); LAS float* d = scr + kk * 33 + 4 * (lane & 7); d[0] = wv[i][0] * gv[i]; d[1] = wv[i][1] * gv[i]; d[2] = wv[i][2] * gv[i]; d[3] = wv[i][3] * gv[i]; } }
;     asm volatile("s_waitcnt lgkmcnt(0)" ::: "memory");
;     const int c = lane & 7; const int r0 = dst_row(dmode, n0);
; #pragma unroll
;     for (int j = 0; j < 4; ++j) { const int n = (lane >> 3) + 8 * j; const LAS float* s = scr + (8 * c) * 33 + n;
;         u32x4 o; o.x = pk2(s[0 * 33], s[1 * 33]); o.y = pk2(s[2 * 33], s[3 * 33]); o.z = pk2(s[4 * 33], s[5 * 33]); o.w = pk2(s[6 * 33], s[7 * 33]);
;         *(u32x4*)(WT + (size_t)(r0 + n) * pitch + k0 + 8 * c) = o; }
.LBB0_134:
	s_andn2_b64 vcc, exec, s[8:9]
	s_cbranch_vccnz .LBB0_136
	s_and_b32 s8, s79, 0x1c0
	s_and_b32 s9, s13, 0x3e0
	s_waitcnt lgkmcnt(3)
	v_or_b32_e32 v4, s8, v140
	s_lshl_b32 s22, s9, 2
	v_lshl_add_u64 v[2:3], v[88:89], 0, s[22:23]
	v_lshlrev_b32_e32 v34, 12, v4
	v_lshl_add_u64 v[30:31], v[2:3], 0, v[34:35]
	s_waitcnt lgkmcnt(2)
	v_add_co_u32_e32 v6, vcc, 0x8000, v30
	v_add_u32_e32 v124, v105, v141
	s_nop 0
	v_addc_co_u32_e32 v7, vcc, 0, v31, vcc
	v_add_co_u32_e32 v10, vcc, 0x10000, v30
	global_load_dwordx4 v[2:5], v[30:31], off
	s_waitcnt lgkmcnt(0)
	global_load_dwordx4 v[6:9], v[6:7], off
	v_addc_co_u32_e32 v11, vcc, 0, v31, vcc
	v_add_co_u32_e32 v14, vcc, 0x18000, v30
	v_add_u32_e32 v126, 0x420, v124
	s_nop 0
	v_addc_co_u32_e32 v15, vcc, 0, v31, vcc
	v_add_co_u32_e32 v18, vcc, s71, v30
	global_load_dwordx4 v[10:13], v[10:11], off
	s_nop 0
	global_load_dwordx4 v[14:17], v[14:15], off
	v_addc_co_u32_e32 v19, vcc, 0, v31, vcc
	v_add_co_u32_e32 v22, vcc, 0x28000, v30
	v_add_u32_e32 v128, 0x428, v124
	s_nop 0
	v_addc_co_u32_e32 v23, vcc, 0, v31, vcc
	global_load_dwordx4 v[18:21], v[18:19], off
	s_nop 0
	global_load_dwordx4 v[22:25], v[22:23], off
	v_add_co_u32_e32 v26, vcc, 0x30000, v30
	v_add_u32_e32 v132, 0x840, v124
	s_nop 0
	v_addc_co_u32_e32 v27, vcc, 0, v31, vcc
	global_load_dwordx4 v[26:29], v[26:27], off
	v_add_co_u32_e32 v30, vcc, 0x38000, v30
	v_add_u32_e32 v134, 0x848, v124
	s_nop 0
	v_addc_co_u32_e32 v31, vcc, 0, v31, vcc
	global_load_dwordx4 v[30:33], v[30:31], off
	v_add_u32_e32 v136, 0xc60, v124
	v_add_u32_e32 v138, 0xc68, v124
	v_add_u32_e32 v156, 0x1080, v124
	v_add_u32_e32 v157, 0x1088, v124
	v_add_u32_e32 v158, 0x14a0, v124
	v_add_u32_e32 v159, 0x14a8, v124
	v_add_u32_e32 v160, 0x18c0, v124
	v_add_u32_e32 v161, 0x18c8, v124
	v_add_u32_e32 v162, 0x1ce0, v124
	v_add_u32_e32 v163, 0x1ce8, v124
	v_or_b32_e32 v34, s9, v140
	s_lshl_b32 s22, s8, 1
	v_lshl_add_u64 v[130:131], v[70:71], 0, s[22:23]
	v_lshlrev_b32_e32 v34, 10, v34
	s_waitcnt vmcnt(7)
	ds_write2_b32 v124, v2, v3 offset1:1
	ds_write2_b32 v124, v4, v5 offset0:2 offset1:3
	s_waitcnt vmcnt(6)
	ds_write2_b32 v126, v6, v7 offset1:1
	ds_write2_b32 v128, v8, v9 offset1:1
	s_waitcnt vmcnt(5)
	ds_write2_b32 v132, v10, v11 offset1:1
	ds_write2_b32 v134, v12, v13 offset1:1
	s_waitcnt vmcnt(4)
	ds_write2_b32 v136, v14, v15 offset1:1
	ds_write2_b32 v138, v16, v17 offset1:1
	s_waitcnt vmcnt(3)
	ds_write2_b32 v156, v18, v19 offset1:1
	ds_write2_b32 v157, v20, v21 offset1:1
	s_waitcnt vmcnt(2)
	ds_write2_b32 v158, v22, v23 offset1:1
	ds_write2_b32 v159, v24, v25 offset1:1
	s_waitcnt vmcnt(1)
	ds_write2_b32 v160, v26, v27 offset1:1
	ds_write2_b32 v161, v28, v29 offset1:1
	s_waitcnt vmcnt(0)
	ds_write2_b32 v162, v30, v31 offset1:1
	ds_write2_b32 v163, v32, v33 offset1:1
	s_waitcnt lgkmcnt(0)
	ds_read2_b32 v[6:7], v155 offset0:33 offset1:41
	ds_read2_b32 v[8:9], v155 offset1:8
	ds_read2_b32 v[10:11], v155 offset0:66 offset1:74
	ds_read2_b32 v[12:13], v155 offset0:99 offset1:107
	ds_read2_b32 v[14:15], v155 offset0:132 offset1:140
	ds_read2_b32 v[16:17], v155 offset0:165 offset1:173
	ds_read2_b32 v[18:19], v155 offset0:198 offset1:206
	ds_read2_b32 v[20:21], v155 offset0:231 offset1:239
	v_lshl_add_u64 v[22:23], v[130:131], 0, v[34:35]
	s_waitcnt lgkmcnt(6)
	v_cvt_pk_bf16_f32 v2, v8, v6
	s_waitcnt lgkmcnt(4)
	v_cvt_pk_bf16_f32 v3, v10, v12
	s_waitcnt lgkmcnt(2)
	v_cvt_pk_bf16_f32 v4, v14, v16
	s_waitcnt lgkmcnt(0)
	v_cvt_pk_bf16_f32 v5, v18, v20
	global_store_dwordx4 v[22:23], v[2:5], off sc1
	v_cvt_pk_bf16_f32 v6, v9, v7
	v_cvt_pk_bf16_f32 v7, v11, v13
	v_cvt_pk_bf16_f32 v8, v15, v17
	v_cvt_pk_bf16_f32 v9, v19, v21
	v_or_b32_e32 v2, s9, v142
	ds_read2_b32 v[10:11], v155 offset0:49 offset1:57
	ds_read2_b32 v[12:13], v155 offset0:16 offset1:24
	ds_read2_b32 v[14:15], v155 offset0:82 offset1:90
	ds_read2_b32 v[16:17], v155 offset0:115 offset1:123
	ds_read2_b32 v[18:19], v155 offset0:148 offset1:156
	ds_read2_b32 v[20:21], v155 offset0:181 offset1:189
	ds_read2_b32 v[22:23], v155 offset0:214 offset1:222
	ds_read2_b32 v[24:25], v155 offset0:247 offset1:255
	v_lshlrev_b32_e32 v34, 10, v2
	v_lshl_add_u64 v[2:3], v[130:131], 0, v[34:35]
	global_store_dwordx4 v[2:3], v[6:9], off sc1
	s_waitcnt lgkmcnt(6)
	v_cvt_pk_bf16_f32 v2, v12, v10
	s_waitcnt lgkmcnt(4)
	v_cvt_pk_bf16_f32 v3, v14, v16
	v_or_b32_e32 v6, s9, v143
	v_lshlrev_b32_e32 v34, 10, v6
	s_waitcnt lgkmcnt(2)
	v_cvt_pk_bf16_f32 v4, v18, v20
	s_waitcnt lgkmcnt(0)
	v_cvt_pk_bf16_f32 v5, v22, v24
	v_lshl_add_u64 v[6:7], v[130:131], 0, v[34:35]
	global_store_dwordx4 v[6:7], v[2:5], off sc1
	v_or_b32_e32 v6, s9, v144
	v_lshlrev_b32_e32 v34, 10, v6
	v_cvt_pk_bf16_f32 v2, v13, v11
	v_cvt_pk_bf16_f32 v3, v15, v17
	v_cvt_pk_bf16_f32 v4, v19, v21
	v_cvt_pk_bf16_f32 v5, v23, v25
	v_lshl_add_u64 v[6:7], v[130:131], 0, v[34:35]
	global_store_dwordx4 v[6:7], v[2:5], off sc1
	s_waitcnt lgkmcnt(0)

; #define LAS __attribute__((address_space(3)))
; __device__ __forceinline__ unsigned pk2(float lo, float hi) { f32x2 v = {lo, hi}; bf2_t b = __builtin_convertvector(v, bf2_t); return __builtin_bit_cast(unsigned, b); }
;     ...
;       for (int i = 0; i < 8; ++i) { const int kk = 8 * i + (lane >> 3); wv[i] = *(const f32x4*)(W + (size_t)(k0 + kk) * N + n0 + 4 * (lane & 7)); gv[i] = gain ? gain[k0 + kk] : 1.0f; }
; #pragma unroll
;       for (int i = 0; i < 8; ++i) { const int kk = 8 * i + (lane >> 3); LAS float* d = scr + kk * 33 + 4 * (lane & 7); d[0] = wv[i][0] * gv[i]; d[1] = wv[i][1] * gv[i]; d[2] = wv[i][2] * gv[i]; d[3] = wv[i][3] * gv[i]; } }
;     asm volatile("s_waitcnt lgkmcnt(0)" ::: "memory");
;     const int c = lane & 7; const int r0 = dst_row(dmode, n0);
; #pragma unroll
;     for (int j = 0; j < 4; ++j) { const int n = (lane >> 3) + 8 * j; const LAS float* s = scr + (8 * c) * 33 + n;
;         u32x4 o; o.x = pk2(s[0 * 33], s[1 * 33]); o.y = pk2(s[2 * 33], s[3 * 33]); o.z = pk2(s[4 * 33], s[5 * 33]); o.w = pk2(s[6 * 33], s[7 * 33]);
;         *(u32x4*)(WT + (size_t)(r0 + n) * pitch + k0 + 8 * c) = o; }
.LBB0_137:
	s_andn2_b64 vcc, exec, s[8:9]
	s_cbranch_vccnz .LBB0_139
	s_and_b32 s8, s79, 0x1c0
	s_and_b32 s9, s13, 0x3e0
	s_waitcnt lgkmcnt(3)
	v_or_b32_e32 v4, s8, v140
	s_lshl_b32 s22, s9, 2
	v_lshl_add_u64 v[2:3], v[90:91], 0, s[22:23]
	v_lshlrev_b32_e32 v34, 12, v4
	v_lshl_add_u64 v[30:31], v[2:3], 0, v[34:35]
	s_waitcnt lgkmcnt(2)
	v_add_co_u32_e32 v6, vcc, 0x8000, v30
	v_add_u32_e32 v124, v105, v141
	s_nop 0
	v_addc_co_u32_e32 v7, vcc, 0, v31, vcc
	v_add_co_u32_e32 v10, vcc, 0x10000, v30
	global_load_dwordx4 v[2:5], v[30:31], off
	s_waitcnt lgkmcnt(0)
	global_load_dwordx4 v[6:9], v[6:7], off
	v_addc_co_u32_e32 v11, vcc, 0, v31, vcc
	v_add_co_u32_e32 v14, vcc, 0x18000, v30
	v_add_u32_e32 v126, 0x420, v124
	s_nop 0
	v_addc_co_u32_e32 v15, vcc, 0, v31, vcc
	v_add_co_u32_e32 v18, vcc, s71, v30
	global_load_dwordx4 v[10:13], v[10:11], off
	s_nop 0
	global_load_dwordx4 v[14:17], v[14:15], off
	v_addc_co_u32_e32 v19, vcc, 0, v31, vcc
	v_add_co_u32_e32 v22, vcc, 0x28000, v30
	v_add_u32_e32 v128, 0x428, v124
	s_nop 0
	v_addc_co_u32_e32 v23, vcc, 0, v31, vcc
	global_load_dwordx4 v[18:21], v[18:19], off
	s_nop 0
	global_load_dwordx4 v[22:25], v[22:23], off
	v_add_co_u32_e32 v26, vcc, 0x30000, v30
	v_add_u32_e32 v132, 0x840, v124
	s_nop 0
	v_addc_co_u32_e32 v27, vcc, 0, v31, vcc
	global_load_dwordx4 v[26:29], v[26:27], off
	v_add_co_u32_e32 v30, vcc, 0x38000, v30
	v_add_u32_e32 v134, 0x848, v124
	s_nop 0
	v_addc_co_u32_e32 v31, vcc, 0, v31, vcc
	global_load_dwordx4 v[30:33], v[30:31], off
	v_add_u32_e32 v136, 0xc60, v124
	v_add_u32_e32 v138, 0xc68, v124
	v_add_u32_e32 v156, 0x1080, v124
	v_add_u32_e32 v157, 0x1088, v124
	v_add_u32_e32 v158, 0x14a0, v124
	v_add_u32_e32 v159, 0x14a8, v124
	v_add_u32_e32 v160, 0x18c0, v124
	v_add_u32_e32 v161, 0x18c8, v124
	v_add_u32_e32 v162, 0x1ce0, v124
	v_add_u32_e32 v163, 0x1ce8, v124
	v_or_b32_e32 v34, s9, v140
	s_lshl_b32 s22, s8, 1
	v_lshl_add_u64 v[130:131], v[82:83], 0, s[22:23]
	v_lshlrev_b32_e32 v34, 10, v34
	s_waitcnt vmcnt(7)
	ds_write2_b32 v124, v2, v3 offset1:1
	ds_write2_b32 v124, v4, v5 offset0:2 offset1:3
	s_waitcnt vmcnt(6)
	ds_write2_b32 v126, v6, v7 offset1:1
	ds_write2_b32 v128, v8, v9 offset1:1
	s_waitcnt vmcnt(5)
	ds_write2_b32 v132, v10, v11 offset1:1
	ds_write2_b32 v134, v12, v13 offset1:1
	s_waitcnt vmcnt(4)
	ds_write2_b32 v136, v14, v15 offset1:1
	ds_write2_b32 v138, v16, v17 offset1:1
	s_waitcnt vmcnt(3)
	ds_write2_b32 v156, v18, v19 offset1:1
	ds_write2_b32 v157, v20, v21 offset1:1
	s_waitcnt vmcnt(2)
	ds_write2_b32 v158, v22, v23 offset1:1
	ds_write2_b32 v159, v24, v25 offset1:1
	s_waitcnt vmcnt(1)
	ds_write2_b32 v160, v26, v27 offset1:1
	ds_write2_b32 v161, v28, v29 offset1:1
	s_waitcnt vmcnt(0)
	ds_write2_b32 v162, v30, v31 offset1:1
	ds_write2_b32 v163, v32, v33 offset1:1
	s_waitcnt lgkmcnt(0)
	ds_read2_b32 v[6:7], v155 offset0:33 offset1:41
	ds_read2_b32 v[8:9], v155 offset1:8
	ds_read2_b32 v[10:11], v155 offset0:66 offset1:74
	ds_read2_b32 v[12:13], v155 offset0:99 offset1:107
	ds_read2_b32 v[14:15], v155 offset0:132 offset1:140
	ds_read2_b32 v[16:17], v155 offset0:165 offset1:173
	ds_read2_b32 v[18:19], v155 offset0:198 offset1:206
	ds_read2_b32 v[20:21], v155 offset0:231 offset1:239
	v_lshl_add_u64 v[22:23], v[130:131], 0, v[34:35]
	s_waitcnt lgkmcnt(6)
	v_cvt_pk_bf16_f32 v2, v8, v6
	s_waitcnt lgkmcnt(4)
	v_cvt_pk_bf16_f32 v3, v10, v12
	s_waitcnt lgkmcnt(2)
	v_cvt_pk_bf16_f32 v4, v14, v16
	s_waitcnt lgkmcnt(0)
	v_cvt_pk_bf16_f32 v5, v18, v20
	global_store_dwordx4 v[22:23], v[2:5], off sc1
	v_cvt_pk_bf16_f32 v6, v9, v7
	v_cvt_pk_bf16_f32 v7, v11, v13
	v_cvt_pk_bf16_f32 v8, v15, v17
	v_cvt_pk_bf16_f32 v9, v19, v21
	v_or_b32_e32 v2, s9, v142
	ds_read2_b32 v[10:11], v155 offset0:49 offset1:57
	ds_read2_b32 v[12:13], v155 offset0:16 offset1:24
	ds_read2_b32 v[14:15], v155 offset0:82 offset1:90
	ds_read2_b32 v[16:17], v155 offset0:115 offset1:123
	ds_read2_b32 v[18:19], v155 offset0:148 offset1:156
	ds_read2_b32 v[20:21], v155 offset0:181 offset1:189
	ds_read2_b32 v[22:23], v155 offset0:214 offset1:222
	ds_read2_b32 v[24:25], v155 offset0:247 offset1:255
	v_lshlrev_b32_e32 v34, 10, v2
	v_lshl_add_u64 v[2:3], v[130:131], 0, v[34:35]
	global_store_dwordx4 v[2:3], v[6:9], off sc1
	s_waitcnt lgkmcnt(6)
	v_cvt_pk_bf16_f32 v2, v12, v10
	s_waitcnt lgkmcnt(4)
	v_cvt_pk_bf16_f32 v3, v14, v16
	v_or_b32_e32 v6, s9, v143
	v_lshlrev_b32_e32 v34, 10, v6
	s_waitcnt lgkmcnt(2)
	v_cvt_pk_bf16_f32 v4, v18, v20
	s_waitcnt lgkmcnt(0)
	v_cvt_pk_bf16_f32 v5, v22, v24
	v_lshl_add_u64 v[6:7], v[130:131], 0, v[34:35]
	global_store_dwordx4 v[6:7], v[2:5], off sc1
	v_or_b32_e32 v6, s9, v144
	v_lshlrev_b32_e32 v34, 10, v6
	v_cvt_pk_bf16_f32 v2, v13, v11
	v_cvt_pk_bf16_f32 v3, v15, v17
	v_cvt_pk_bf16_f32 v4, v19, v21
	v_cvt_pk_bf16_f32 v5, v23, v25
	v_lshl_add_u64 v[6:7], v[130:131], 0, v[34:35]
	global_store_dwordx4 v[6:7], v[2:5], off sc1
	s_waitcnt lgkmcnt(0)

; __device__ __forceinline__ unsigned cvt_pk_bf16(float lo, float hi) { f32x2 v = {lo, hi}; bf2_t b = __builtin_convertvector(v, bf2_t); return __builtin_bit_cast(unsigned, b); }
;     __device__ __forceinline__ bool operator()(f32x4 (&acc)[2][2][4][2], const Unit& u, int wr, int wc, int fr, int fq) const {
;     ...
;             const float qs = isq ? QS : 1.f;
;     ...
;                     for (int bj = 0; bj < 2; ++bj) { const f32x4 a = v[bj][0] * qs, b = v[bj][1] * qs;
;                         u32x4 w; w.x = cvt_pk_bf16(a[0], a[1]); w.y = cvt_pk_bf16(a[2], a[3]); w.z = cvt_pk_bf16(b[0], b[1]); w.w = cvt_pk_bf16(b[2], b[3]);
;                         *(u32x4*)(O + (size_t)row * ldo + pn * BM + 64 * wc + 32 * bj + 8 * fq) = w; } }
.LBB0_624:
	s_cmp_lt_i32 s46, 2
	s_cselect_b64 s[48:49], -1, 0
	s_cmp_lt_u32 s39, 3
	s_cselect_b64 s[52:53], -1, 0
	s_or_b64 s[48:49], s[48:49], s[52:53]
	s_or_b64 vcc, s[4:5], s[48:49]
	v_cndmask_b32_e32 v130, 1.0, v180, vcc
	v_mov_b32_e32 v131, v130
	v_pk_mul_f32 v[142:143], v[130:131], v[142:143] op_sel_hi:[0,1]
	s_lshl_b32 s48, s46, 8
	v_pk_mul_f32 v[188:189], v[130:131], v[140:141] op_sel_hi:[0,1]
	v_pk_mul_f32 v[140:141], v[130:131], v[138:139] op_sel_hi:[0,1]
	v_cvt_pk_bf16_f32 v138, v142, v143
	v_lshlrev_b64 v[142:143], 13, v[166:167]
	s_ashr_i32 s49, s48, 31
	v_lshl_add_u64 v[142:143], s[20:21], 0, v[142:143]
	v_lshl_add_u64 v[142:143], s[48:49], 1, v[142:143]
	v_pk_mul_f32 v[144:145], v[130:131], v[144:145] op_sel_hi:[0,1]
	v_lshl_add_u64 v[142:143], v[142:143], 0, s[16:17]
	v_cvt_pk_bf16_f32 v139, v144, v145
	v_cvt_pk_bf16_f32 v140, v140, v141
	v_cvt_pk_bf16_f32 v141, v188, v189
	v_lshl_add_u64 v[142:143], v[164:165], 1, v[142:143]
	global_store_dwordx4 v[142:143], v[138:141], off sc1
	v_pk_mul_f32 v[136:137], v[130:131], v[136:137] op_sel_hi:[0,1]
	v_pk_mul_f32 v[144:145], v[130:131], v[170:171] op_sel_hi:[0,1]
	v_pk_mul_f32 v[138:139], v[130:131], v[168:169] op_sel_hi:[0,1]
	v_pk_mul_f32 v[140:141], v[130:131], v[134:135] op_sel_hi:[0,1]
	v_cvt_pk_bf16_f32 v134, v138, v139
	v_cvt_pk_bf16_f32 v135, v136, v137
	v_cvt_pk_bf16_f32 v136, v144, v145
	v_cvt_pk_bf16_f32 v137, v140, v141
	s_cmp_lt_i32 s46, 15
	global_store_dwordx4 v[142:143], v[134:137], off offset:64 sc1
	s_cbranch_scc1 .LBB0_626
	s_cmp_eq_u32 s46, 15
	s_cselect_b64 s[4:5], -1, 0
	s_cbranch_execz .LBB0_627
	s_branch .LBB0_628

; __device__ __forceinline__ unsigned cvt_pk_bf16(float lo, float hi) { f32x2 v = {lo, hi}; bf2_t b = __builtin_convertvector(v, bf2_t); return __builtin_bit_cast(unsigned, b); }
;     __device__ __forceinline__ bool operator()(f32x4 (&acc)[2][2][4][2], const Unit& u, int wr, int wc, int fr, int fq) const {
;     ...
;                     for (int bj = 0; bj < 2; ++bj) { const f32x4 a = v[bj][0] * qs, b = v[bj][1] * qs;
;                         u32x4 w; w.x = cvt_pk_bf16(a[0], a[1]); w.y = cvt_pk_bf16(a[2], a[3]); w.z = cvt_pk_bf16(b[0], b[1]); w.w = cvt_pk_bf16(b[2], b[3]);
;                         *(u32x4*)(O + (size_t)row * ldo + pn * BM + 64 * wc + 32 * bj + 8 * fq) = w; } }
.LBB0_632:
	v_ashrrev_i32_e32 v135, 31, v134
	v_mov_b32_e32 v136, v130
	v_mov_b32_e32 v137, v130
	v_pk_mul_f32 v[126:127], v[130:131], v[126:127]
	v_pk_mul_f32 v[138:139], v[136:137], v[124:125]
	v_pk_mul_f32 v[124:125], v[130:131], v[122:123]
	v_cvt_pk_bf16_f32 v122, v126, v127
	v_lshlrev_b64 v[126:127], 13, v[134:135]
	v_lshl_add_u64 v[126:127], s[20:21], 0, v[126:127]
	v_lshl_add_u64 v[126:127], s[48:49], 1, v[126:127]
	v_pk_mul_f32 v[128:129], v[136:137], v[128:129]
	v_lshl_add_u64 v[126:127], v[126:127], 0, s[16:17]
	v_cvt_pk_bf16_f32 v123, v128, v129
	v_cvt_pk_bf16_f32 v124, v124, v125
	v_cvt_pk_bf16_f32 v125, v138, v139
	v_lshl_add_u64 v[126:127], v[164:165], 1, v[126:127]
	global_store_dwordx4 v[126:127], v[122:125], off sc1
	v_pk_mul_f32 v[120:121], v[136:137], v[120:121]
	v_pk_mul_f32 v[118:119], v[130:131], v[118:119]
	v_pk_mul_f32 v[122:123], v[136:137], v[116:117]
	v_pk_mul_f32 v[116:117], v[130:131], v[114:115]
	v_cvt_pk_bf16_f32 v114, v118, v119
	v_cvt_pk_bf16_f32 v115, v120, v121
	v_cvt_pk_bf16_f32 v116, v116, v117
	v_cvt_pk_bf16_f32 v117, v122, v123
	s_cmp_lt_i32 s46, 15
	global_store_dwordx4 v[126:127], v[114:117], off offset:64 sc1
	s_cbranch_scc1 .LBB0_634
	s_cmp_eq_u32 s46, 15
	s_cselect_b64 s[50:51], -1, 0
	s_cbranch_execz .LBB0_635
	s_branch .LBB0_636

; __device__ __forceinline__ unsigned cvt_pk_bf16(float lo, float hi) { f32x2 v = {lo, hi}; bf2_t b = __builtin_convertvector(v, bf2_t); return __builtin_bit_cast(unsigned, b); }
;     __device__ __forceinline__ bool operator()(f32x4 (&acc)[2][2][4][2], const Unit& u, int wr, int wc, int fr, int fq) const {
;     ...
;                     for (int bj = 0; bj < 2; ++bj) { const f32x4 a = v[bj][0] * qs, b = v[bj][1] * qs;
;                         u32x4 w; w.x = cvt_pk_bf16(a[0], a[1]); w.y = cvt_pk_bf16(a[2], a[3]); w.z = cvt_pk_bf16(b[0], b[1]); w.w = cvt_pk_bf16(b[2], b[3]);
;                         *(u32x4*)(O + (size_t)row * ldo + pn * BM + 64 * wc + 32 * bj + 8 * fq) = w; } }
.LBB0_640:
	v_ashrrev_i32_e32 v115, 31, v114
	v_mov_b32_e32 v116, v130
	v_mov_b32_e32 v117, v130
	v_pk_mul_f32 v[110:111], v[130:131], v[110:111]
	v_pk_mul_f32 v[118:119], v[116:117], v[108:109]
	v_pk_mul_f32 v[108:109], v[130:131], v[106:107]
	v_cvt_pk_bf16_f32 v106, v110, v111
	v_lshlrev_b64 v[110:111], 13, v[114:115]
	v_lshl_add_u64 v[110:111], s[20:21], 0, v[110:111]
	v_lshl_add_u64 v[110:111], s[48:49], 1, v[110:111]
	v_pk_mul_f32 v[112:113], v[116:117], v[112:113]
	v_lshl_add_u64 v[110:111], v[110:111], 0, s[16:17]
	v_cvt_pk_bf16_f32 v107, v112, v113
	v_cvt_pk_bf16_f32 v108, v108, v109
	v_cvt_pk_bf16_f32 v109, v118, v119
	v_lshl_add_u64 v[110:111], v[164:165], 1, v[110:111]
	global_store_dwordx4 v[110:111], v[106:109], off sc1
	v_pk_mul_f32 v[104:105], v[116:117], v[104:105]
	v_pk_mul_f32 v[102:103], v[130:131], v[102:103]
	v_pk_mul_f32 v[106:107], v[116:117], v[100:101]
	v_pk_mul_f32 v[100:101], v[130:131], v[98:99]
	v_cvt_pk_bf16_f32 v98, v102, v103
	v_cvt_pk_bf16_f32 v99, v104, v105
	v_cvt_pk_bf16_f32 v100, v100, v101
	v_cvt_pk_bf16_f32 v101, v106, v107
	s_cmp_lt_i32 s46, 15
	global_store_dwordx4 v[110:111], v[98:101], off offset:64 sc1
	s_cbranch_scc1 .LBB0_642
	s_cmp_eq_u32 s46, 15
	s_cselect_b64 s[50:51], -1, 0
	s_cbranch_execz .LBB0_643
	s_branch .LBB0_644

; __device__ __forceinline__ unsigned cvt_pk_bf16(float lo, float hi) { f32x2 v = {lo, hi}; bf2_t b = __builtin_convertvector(v, bf2_t); return __builtin_bit_cast(unsigned, b); }
;     __device__ __forceinline__ bool operator()(f32x4 (&acc)[2][2][4][2], const Unit& u, int wr, int wc, int fr, int fq) const {
;     ...
;                     for (int bj = 0; bj < 2; ++bj) { const f32x4 a = v[bj][0] * qs, b = v[bj][1] * qs;
;                         u32x4 w; w.x = cvt_pk_bf16(a[0], a[1]); w.y = cvt_pk_bf16(a[2], a[3]); w.z = cvt_pk_bf16(b[0], b[1]); w.w = cvt_pk_bf16(b[2], b[3]);
;                         *(u32x4*)(O + (size_t)row * ldo + pn * BM + 64 * wc + 32 * bj + 8 * fq) = w; } }
.LBB0_648:
	v_ashrrev_i32_e32 v99, 31, v98
	v_mov_b32_e32 v100, v130
	v_mov_b32_e32 v101, v130
	v_pk_mul_f32 v[94:95], v[130:131], v[94:95]
	v_pk_mul_f32 v[102:103], v[100:101], v[92:93]
	v_pk_mul_f32 v[92:93], v[130:131], v[90:91]
	v_cvt_pk_bf16_f32 v90, v94, v95
	v_lshlrev_b64 v[94:95], 13, v[98:99]
	v_lshl_add_u64 v[94:95], s[20:21], 0, v[94:95]
	v_lshl_add_u64 v[94:95], s[48:49], 1, v[94:95]
	v_pk_mul_f32 v[96:97], v[100:101], v[96:97]
	v_lshl_add_u64 v[94:95], v[94:95], 0, s[16:17]
	v_cvt_pk_bf16_f32 v91, v96, v97
	v_cvt_pk_bf16_f32 v92, v92, v93
	v_cvt_pk_bf16_f32 v93, v102, v103
	v_lshl_add_u64 v[94:95], v[164:165], 1, v[94:95]
	global_store_dwordx4 v[94:95], v[90:93], off sc1
	v_pk_mul_f32 v[88:89], v[100:101], v[88:89]
	v_pk_mul_f32 v[86:87], v[130:131], v[86:87]
	v_pk_mul_f32 v[90:91], v[100:101], v[84:85]
	v_pk_mul_f32 v[84:85], v[130:131], v[82:83]
	v_cvt_pk_bf16_f32 v82, v86, v87
	v_cvt_pk_bf16_f32 v83, v88, v89
	v_cvt_pk_bf16_f32 v84, v84, v85
	v_cvt_pk_bf16_f32 v85, v90, v91
	s_cmp_lt_i32 s46, 15
	global_store_dwordx4 v[94:95], v[82:85], off offset:64 sc1
	s_cbranch_scc1 .LBB0_650
	s_cmp_eq_u32 s46, 15
	s_cselect_b64 s[50:51], -1, 0
	s_cbranch_execz .LBB0_651
	s_branch .LBB0_652

; __device__ __forceinline__ unsigned cvt_pk_bf16(float lo, float hi) { f32x2 v = {lo, hi}; bf2_t b = __builtin_convertvector(v, bf2_t); return __builtin_bit_cast(unsigned, b); }
;     __device__ __forceinline__ bool operator()(f32x4 (&acc)[2][2][4][2], const Unit& u, int wr, int wc, int fr, int fq) const {
;     ...
;                     for (int bj = 0; bj < 2; ++bj) { const f32x4 a = v[bj][0] * qs, b = v[bj][1] * qs;
;                         u32x4 w; w.x = cvt_pk_bf16(a[0], a[1]); w.y = cvt_pk_bf16(a[2], a[3]); w.z = cvt_pk_bf16(b[0], b[1]); w.w = cvt_pk_bf16(b[2], b[3]);
;                         *(u32x4*)(O + (size_t)row * ldo + pn * BM + 64 * wc + 32 * bj + 8 * fq) = w; } }
.LBB0_656:
	v_ashrrev_i32_e32 v83, 31, v82
	v_mov_b32_e32 v84, v130
	v_mov_b32_e32 v85, v130
	v_pk_mul_f32 v[78:79], v[130:131], v[78:79]
	v_pk_mul_f32 v[86:87], v[84:85], v[76:77]
	v_pk_mul_f32 v[76:77], v[130:131], v[74:75]
	v_cvt_pk_bf16_f32 v74, v78, v79
	v_lshlrev_b64 v[78:79], 13, v[82:83]
	v_lshl_add_u64 v[78:79], s[20:21], 0, v[78:79]
	v_lshl_add_u64 v[78:79], s[48:49], 1, v[78:79]
	v_pk_mul_f32 v[80:81], v[84:85], v[80:81]
	v_lshl_add_u64 v[78:79], v[78:79], 0, s[16:17]
	v_cvt_pk_bf16_f32 v75, v80, v81
	v_cvt_pk_bf16_f32 v76, v76, v77
	v_cvt_pk_bf16_f32 v77, v86, v87
	v_lshl_add_u64 v[78:79], v[164:165], 1, v[78:79]
	global_store_dwordx4 v[78:79], v[74:77], off sc1
	v_pk_mul_f32 v[72:73], v[84:85], v[72:73]
	v_pk_mul_f32 v[70:71], v[130:131], v[70:71]
	v_pk_mul_f32 v[74:75], v[84:85], v[68:69]
	v_pk_mul_f32 v[68:69], v[130:131], v[66:67]
	v_cvt_pk_bf16_f32 v66, v70, v71
	v_cvt_pk_bf16_f32 v67, v72, v73
	v_cvt_pk_bf16_f32 v68, v68, v69
	v_cvt_pk_bf16_f32 v69, v74, v75
	s_cmp_lt_i32 s46, 15
	global_store_dwordx4 v[78:79], v[66:69], off offset:64 sc1
	s_cbranch_scc1 .LBB0_658
	s_cmp_eq_u32 s46, 15
	s_cselect_b64 s[50:51], -1, 0
	s_cbranch_execz .LBB0_659
	s_branch .LBB0_660

; __device__ __forceinline__ unsigned cvt_pk_bf16(float lo, float hi) { f32x2 v = {lo, hi}; bf2_t b = __builtin_convertvector(v, bf2_t); return __builtin_bit_cast(unsigned, b); }
;     __device__ __forceinline__ bool operator()(f32x4 (&acc)[2][2][4][2], const Unit& u, int wr, int wc, int fr, int fq) const {
;     ...
;                     for (int bj = 0; bj < 2; ++bj) { const f32x4 a = v[bj][0] * qs, b = v[bj][1] * qs;
;                         u32x4 w; w.x = cvt_pk_bf16(a[0], a[1]); w.y = cvt_pk_bf16(a[2], a[3]); w.z = cvt_pk_bf16(b[0], b[1]); w.w = cvt_pk_bf16(b[2], b[3]);
;                         *(u32x4*)(O + (size_t)row * ldo + pn * BM + 64 * wc + 32 * bj + 8 * fq) = w; } }
.LBB0_664:
	v_ashrrev_i32_e32 v67, 31, v66
	v_mov_b32_e32 v68, v130
	v_mov_b32_e32 v69, v130
	v_pk_mul_f32 v[46:47], v[130:131], v[46:47]
	v_pk_mul_f32 v[70:71], v[68:69], v[44:45]
	v_pk_mul_f32 v[44:45], v[130:131], v[42:43]
	v_cvt_pk_bf16_f32 v42, v46, v47
	v_lshlrev_b64 v[46:47], 13, v[66:67]
	v_lshl_add_u64 v[46:47], s[20:21], 0, v[46:47]
	v_lshl_add_u64 v[46:47], s[48:49], 1, v[46:47]
	v_pk_mul_f32 v[48:49], v[68:69], v[48:49]
	v_lshl_add_u64 v[46:47], v[46:47], 0, s[16:17]
	v_cvt_pk_bf16_f32 v43, v48, v49
	v_cvt_pk_bf16_f32 v44, v44, v45
	v_cvt_pk_bf16_f32 v45, v70, v71
	v_lshl_add_u64 v[46:47], v[164:165], 1, v[46:47]
	global_store_dwordx4 v[46:47], v[42:45], off sc1
	v_pk_mul_f32 v[40:41], v[68:69], v[40:41]
	v_pk_mul_f32 v[38:39], v[130:131], v[38:39]
	v_pk_mul_f32 v[42:43], v[68:69], v[36:37]
	v_pk_mul_f32 v[36:37], v[130:131], v[34:35]
	v_cvt_pk_bf16_f32 v34, v38, v39
	v_cvt_pk_bf16_f32 v35, v40, v41
	v_cvt_pk_bf16_f32 v36, v36, v37
	v_cvt_pk_bf16_f32 v37, v42, v43
	s_cmp_lt_i32 s46, 15
	global_store_dwordx4 v[46:47], v[34:37], off offset:64 sc1
	s_cbranch_scc1 .LBB0_666
	s_cmp_eq_u32 s46, 15
	s_cselect_b64 s[50:51], -1, 0
	s_cbranch_execz .LBB0_667
	s_branch .LBB0_668

; __device__ __forceinline__ unsigned cvt_pk_bf16(float lo, float hi) { f32x2 v = {lo, hi}; bf2_t b = __builtin_convertvector(v, bf2_t); return __builtin_bit_cast(unsigned, b); }
;     __device__ __forceinline__ bool operator()(f32x4 (&acc)[2][2][4][2], const Unit& u, int wr, int wc, int fr, int fq) const {
;     ...
;                     for (int bj = 0; bj < 2; ++bj) { const f32x4 a = v[bj][0] * qs, b = v[bj][1] * qs;
;                         u32x4 w; w.x = cvt_pk_bf16(a[0], a[1]); w.y = cvt_pk_bf16(a[2], a[3]); w.z = cvt_pk_bf16(b[0], b[1]); w.w = cvt_pk_bf16(b[2], b[3]);
;                         *(u32x4*)(O + (size_t)row * ldo + pn * BM + 64 * wc + 32 * bj + 8 * fq) = w; } }
.LBB0_672:
	v_ashrrev_i32_e32 v35, 31, v34
	v_mov_b32_e32 v36, v130
	v_mov_b32_e32 v37, v130
	v_pk_mul_f32 v[30:31], v[130:131], v[30:31]
	v_pk_mul_f32 v[38:39], v[36:37], v[28:29]
	v_pk_mul_f32 v[28:29], v[130:131], v[26:27]
	v_cvt_pk_bf16_f32 v26, v30, v31
	v_lshlrev_b64 v[30:31], 13, v[34:35]
	v_lshl_add_u64 v[30:31], s[20:21], 0, v[30:31]
	v_lshl_add_u64 v[30:31], s[48:49], 1, v[30:31]
	v_pk_mul_f32 v[32:33], v[36:37], v[32:33]
	v_lshl_add_u64 v[30:31], v[30:31], 0, s[16:17]
	v_cvt_pk_bf16_f32 v27, v32, v33
	v_cvt_pk_bf16_f32 v28, v28, v29
	v_cvt_pk_bf16_f32 v29, v38, v39
	v_lshl_add_u64 v[30:31], v[164:165], 1, v[30:31]
	global_store_dwordx4 v[30:31], v[26:29], off sc1
	v_pk_mul_f32 v[24:25], v[36:37], v[24:25]
	v_pk_mul_f32 v[22:23], v[130:131], v[22:23]
	v_pk_mul_f32 v[26:27], v[36:37], v[20:21]
	v_pk_mul_f32 v[20:21], v[130:131], v[18:19]
	v_cvt_pk_bf16_f32 v18, v22, v23
	v_cvt_pk_bf16_f32 v19, v24, v25
	v_cvt_pk_bf16_f32 v20, v20, v21
	v_cvt_pk_bf16_f32 v21, v26, v27
	s_cmp_lt_i32 s46, 15
	global_store_dwordx4 v[30:31], v[18:21], off offset:64 sc1
	s_cbranch_scc1 .LBB0_674
	s_cmp_eq_u32 s46, 15
	s_cselect_b64 s[46:47], -1, 0
	s_cbranch_execz .LBB0_675
	s_branch .LBB0_676

; __device__ __forceinline__ unsigned cvt_pk_bf16(float lo, float hi) { f32x2 v = {lo, hi}; bf2_t b = __builtin_convertvector(v, bf2_t); return __builtin_bit_cast(unsigned, b); }
;     __device__ __forceinline__ bool operator()(f32x4 (&acc)[2][2][4][2], const Unit& u, int wr, int wc, int fr, int fq) const {
;     ...
;                     for (int bj = 0; bj < 2; ++bj) { const f32x4 a = v[bj][0] * qs, b = v[bj][1] * qs;
;                         u32x4 w; w.x = cvt_pk_bf16(a[0], a[1]); w.y = cvt_pk_bf16(a[2], a[3]); w.z = cvt_pk_bf16(b[0], b[1]); w.w = cvt_pk_bf16(b[2], b[3]);
;                         *(u32x4*)(O + (size_t)row * ldo + pn * BM + 64 * wc + 32 * bj + 8 * fq) = w; } }
.LBB0_680:
	v_ashrrev_i32_e32 v19, 31, v18
	v_mov_b32_e32 v20, v130
	v_mov_b32_e32 v21, v130
	v_pk_mul_f32 v[14:15], v[130:131], v[14:15]
	v_pk_mul_f32 v[22:23], v[20:21], v[12:13]
	v_pk_mul_f32 v[12:13], v[130:131], v[10:11]
	v_cvt_pk_bf16_f32 v10, v14, v15
	v_lshlrev_b64 v[14:15], 13, v[18:19]
	v_lshl_add_u64 v[14:15], s[20:21], 0, v[14:15]
	v_lshl_add_u64 v[14:15], s[48:49], 1, v[14:15]
	v_pk_mul_f32 v[16:17], v[20:21], v[16:17]
	v_lshl_add_u64 v[14:15], v[14:15], 0, s[16:17]
	v_cvt_pk_bf16_f32 v11, v16, v17
	v_cvt_pk_bf16_f32 v12, v12, v13
	v_cvt_pk_bf16_f32 v13, v22, v23
	v_lshl_add_u64 v[14:15], v[164:165], 1, v[14:15]
	global_store_dwordx4 v[14:15], v[10:13], off sc1
	v_pk_mul_f32 v[8:9], v[20:21], v[8:9]
	v_pk_mul_f32 v[6:7], v[130:131], v[6:7]
	v_pk_mul_f32 v[10:11], v[20:21], v[4:5]
	v_pk_mul_f32 v[4:5], v[130:131], v[2:3]
	v_cvt_pk_bf16_f32 v2, v6, v7
	v_cvt_pk_bf16_f32 v3, v8, v9
	v_cvt_pk_bf16_f32 v4, v4, v5
	v_cvt_pk_bf16_f32 v5, v10, v11
	s_andn2_b64 vcc, exec, s[2:3]
	s_mov_b64 s[2:3], -1
	global_store_dwordx4 v[14:15], v[2:5], off offset:64 sc1
	s_cbranch_vccnz .LBB0_581
	s_andn2_b64 vcc, exec, s[18:19]
	s_cbranch_vccnz .LBB0_580
	s_barrier
	s_branch .LBB0_580

; #define LAS __attribute__((address_space(3)))
; __device__ __forceinline__ unsigned cvtpk(float lo, float hi) { f32x2 v = {lo, hi}; bf2_t b = __builtin_convertvector(v, bf2_t); return __builtin_bit_cast(unsigned, b); }
; __device__ __forceinline__ void store_ot2(bf16_t* row0, size_t stride, const f32x16 (&o)[2], float sc, LAS unsigned char* kl, int lane) {
;     const int r = lane & 31, hh = lane >> 5;
; #pragma unroll
;     for (int dh = 0; dh < 2; ++dh)
; #pragma unroll
;         for (int g = 0; g < 4; ++g) { u32x2 w; w.x = cvtpk(o[dh][4 * g] * sc, o[dh][4 * g + 1] * sc); w.y = cvtpk(o[dh][4 * g + 2] * sc, o[dh][4 * g + 3] * sc);
;             *(LAS u32x2*)(kl + r * VL_PITCH + (32 * dh + 8 * g + 4 * hh) * 2) = w; }
; #pragma unroll
;     for (int i = 0; i < 4; ++i) { const int id = lane + 64 * i; const u32x4 v = *(const LAS u32x4*)(kl + (id >> 3) * VL_PITCH + (id & 7) * 16); *(u32x4*)(row0 + (size_t)(id >> 3) * stride + (id & 7) * 8) = v; }
; }
.LBB0_795:
	s_waitcnt vmcnt(7)
	v_cvt_pk_bf16_f32 v51, v16, v17
	v_add_u32_e32 v3, v173, v214
	ds_write_b64 v3, v[50:51] offset:4720
	v_add_u32_e32 v3, v215, v167
	ds_read_b128 v[10:13], v3 offset:4608
	ds_read_b128 v[14:17], v216 offset:4608
	v_mov_b32_e32 v189, v149
	v_lshl_add_u64 v[18:19], s[38:39], 0, v[188:189]
	v_lshlrev_b32_e32 v148, 1, v8
	v_lshl_add_u64 v[8:9], v[18:19], 0, v[148:149]
	v_lshlrev_b32_e32 v148, 1, v6
	s_waitcnt lgkmcnt(1)
	global_store_dwordx4 v[8:9], v[10:13], off sc1
	ds_read_b128 v[6:9], v216 offset:5760
	s_nop 0
	v_lshl_add_u64 v[10:11], v[18:19], 0, v[148:149]
	s_waitcnt lgkmcnt(1)
	global_store_dwordx4 v[10:11], v[14:17], off sc1
	ds_read_b128 v[10:13], v216 offset:6912
	v_lshlrev_b32_e32 v148, 1, v4
	v_lshl_add_u64 v[4:5], v[18:19], 0, v[148:149]
	v_lshlrev_b32_e32 v148, 1, v2
	v_lshl_add_u64 v[2:3], v[18:19], 0, v[148:149]
	s_waitcnt lgkmcnt(1)
	global_store_dwordx4 v[4:5], v[6:9], off sc1
	s_waitcnt lgkmcnt(0)
	global_store_dwordx4 v[2:3], v[10:13], off sc1
	s_branch .LBB0_753
